# rotated k-loop schedule applied to all seven GEMM loops (P2, merge x2, out-proj, MoE1, MoE2)
# speedup vs baseline: 1.0222x; 1.0053x over previous
; template <class MK, class SW, class EPI>
; __device__ __forceinline__ void gemm_phase(int first, int step, int n, int nk, MK mk, SW swapf, EPI epi, char* lds) {
;     ...
;   TP cur = mk(first);
;   gemm_issue3(cur, lds);
; #pragma unroll 1
;   for (int it = first; it < n; it += step) {
;     const bool has_next = (it + step < n);
;     const TP nxt = mk(has_next ? it + step : it);
;     f32x4 acc[8][4];
;     zero_acc(acc);
;     if (swapf(it)) gemm_main<true>(acc, cur, nk, lds); else gemm_main<false>(acc, cur, nk, lds);
; __device__ __forceinline__ void zero_acc(f32x4 (&acc)[8][4]) {
; #pragma unroll
;   for (int i = 0; i < 8; ++i)
; #pragma unroll
;     for (int j = 0; j < 4; ++j) acc[i][j] = (f32x4){0.f, 0.f, 0.f, 0.f};
.LBB0_385:
	s_mov_b64 s[34:35], -1
	s_andn2_b64 vcc, exec, s[36:37]
	v_lshl_add_u64 v[128:129], v[158:159], 0, s[20:21]
	v_lshl_add_u64 v[130:131], v[156:157], 0, s[20:21]
	v_lshl_add_u64 v[132:133], v[146:147], 0, s[20:21]
	v_lshl_add_u64 v[134:135], v[160:161], 0, s[20:21]
	s_cbranch_vccz .LBB0_401
	v_mov_b32_e32 v0, v153
	v_lshl_add_u64 v[136:137], v[158:159], 0, s[20:21]
	v_lshlrev_b32_e32 v3, 2, v0
	v_and_b32_e32 v3, 48, v3
	v_sub_u32_e32 v3, 0, v3
	v_and_b32_e32 v164, 15, v0
	v_lshlrev_b32_e32 v1, 5, v0
	v_lshlrev_b32_e32 v2, 4, v0
	v_bitop3_b32 v165, v0, 48, v3 bitop3:0x48
	v_ashrrev_i32_e32 v166, 1, v0
	v_lshlrev_b32_e32 v0, 6, v0
	v_and_b32_e32 v1, 0xfffff800, v1
	v_and_b32_e32 v2, 0x3f0, v2
	v_and_or_b32 v3, v166, s41, v164
	v_and_b32_e32 v167, 0x33c0, v0
	v_mov_b32_e32 v0, 0
	v_lshl_or_b32 v168, v3, 6, v165
	v_or_b32_e32 v170, v167, v165
	v_add3_u32 v171, 0, v1, v2
	v_lshl_add_u64 v[138:139], v[156:157], 0, s[20:21]
	v_lshl_add_u64 v[140:141], v[146:147], 0, s[20:21]
	v_lshl_add_u64 v[142:143], v[160:161], 0, s[20:21]
	s_mov_b32 s34, 0x18000
	v_mov_b32_e32 v1, v0
	v_mov_b32_e32 v2, v0
	v_mov_b32_e32 v3, v0
	v_mov_b32_e32 v4, v0
	v_mov_b32_e32 v5, v0
	v_mov_b32_e32 v6, v0
	v_mov_b32_e32 v7, v0
	v_mov_b32_e32 v8, v0
	v_mov_b32_e32 v9, v0
	v_mov_b32_e32 v10, v0
	v_mov_b32_e32 v11, v0
	v_mov_b32_e32 v12, v0
	v_mov_b32_e32 v13, v0
	v_mov_b32_e32 v14, v0
	v_mov_b32_e32 v15, v0
	v_mov_b32_e32 v16, v0
	v_mov_b32_e32 v17, v0
	v_mov_b32_e32 v18, v0
	v_mov_b32_e32 v19, v0
	v_mov_b32_e32 v20, v0
	v_mov_b32_e32 v21, v0
	v_mov_b32_e32 v22, v0
	v_mov_b32_e32 v23, v0
	v_mov_b32_e32 v24, v0
	v_mov_b32_e32 v25, v0
	v_mov_b32_e32 v26, v0
	v_mov_b32_e32 v27, v0
	v_mov_b32_e32 v28, v0
	v_mov_b32_e32 v29, v0
	v_mov_b32_e32 v30, v0
	v_mov_b32_e32 v31, v0
	v_mov_b32_e32 v32, v0
	v_mov_b32_e32 v33, v0
	v_mov_b32_e32 v34, v0
	v_mov_b32_e32 v35, v0
	v_mov_b32_e32 v36, v0
	v_mov_b32_e32 v37, v0
	v_mov_b32_e32 v38, v0
	v_mov_b32_e32 v39, v0
	v_mov_b32_e32 v40, v0
	v_mov_b32_e32 v41, v0
	v_mov_b32_e32 v42, v0
	v_mov_b32_e32 v43, v0
	v_mov_b32_e32 v44, v0
	v_mov_b32_e32 v45, v0
	v_mov_b32_e32 v46, v0
	v_mov_b32_e32 v47, v0
	v_mov_b32_e32 v48, v0
	v_mov_b32_e32 v49, v0
	v_mov_b32_e32 v50, v0
	v_mov_b32_e32 v51, v0
	v_mov_b32_e32 v52, v0
	v_mov_b32_e32 v53, v0
	v_mov_b32_e32 v54, v0
	v_mov_b32_e32 v55, v0
	v_mov_b32_e32 v56, v0
	v_mov_b32_e32 v57, v0
	v_mov_b32_e32 v58, v0
	v_mov_b32_e32 v59, v0
	v_mov_b32_e32 v60, v0
	v_mov_b32_e32 v61, v0
	v_mov_b32_e32 v62, v0
	v_mov_b32_e32 v63, v0
	v_mov_b32_e32 v64, v0
	v_mov_b32_e32 v65, v0
	v_mov_b32_e32 v66, v0
	v_mov_b32_e32 v67, v0
	v_mov_b32_e32 v68, v0
	v_mov_b32_e32 v69, v0
	v_mov_b32_e32 v70, v0
	v_mov_b32_e32 v71, v0
	v_mov_b32_e32 v72, v0
	v_mov_b32_e32 v73, v0
	v_mov_b32_e32 v74, v0
	v_mov_b32_e32 v75, v0
	v_mov_b32_e32 v76, v0
	v_mov_b32_e32 v77, v0
	v_mov_b32_e32 v78, v0
	v_mov_b32_e32 v79, v0
	v_mov_b32_e32 v80, v0
	v_mov_b32_e32 v81, v0
	v_mov_b32_e32 v82, v0
	v_mov_b32_e32 v83, v0
	v_mov_b32_e32 v84, v0
	v_mov_b32_e32 v85, v0
	v_mov_b32_e32 v86, v0
	v_mov_b32_e32 v87, v0
	v_mov_b32_e32 v88, v0
	v_mov_b32_e32 v89, v0
	v_mov_b32_e32 v90, v0
	v_mov_b32_e32 v91, v0
	v_mov_b32_e32 v92, v0
	v_mov_b32_e32 v93, v0
	v_mov_b32_e32 v94, v0
	v_mov_b32_e32 v95, v0
	v_mov_b32_e32 v96, v0
	v_mov_b32_e32 v97, v0
	v_mov_b32_e32 v98, v0
	v_mov_b32_e32 v99, v0
	v_mov_b32_e32 v100, v0
	v_mov_b32_e32 v101, v0
	v_mov_b32_e32 v102, v0
	v_mov_b32_e32 v103, v0
	v_mov_b32_e32 v104, v0
	v_mov_b32_e32 v105, v0
	v_mov_b32_e32 v106, v0
	v_mov_b32_e32 v107, v0
	v_mov_b32_e32 v108, v0
	v_mov_b32_e32 v109, v0
	v_mov_b32_e32 v110, v0
	v_mov_b32_e32 v111, v0
	v_mov_b32_e32 v112, v0
	v_mov_b32_e32 v113, v0
	v_mov_b32_e32 v114, v0
	v_mov_b32_e32 v115, v0
	v_mov_b32_e32 v116, v0
	v_mov_b32_e32 v117, v0
	v_mov_b32_e32 v118, v0
	v_mov_b32_e32 v119, v0
	v_mov_b32_e32 v120, v0
	v_mov_b32_e32 v121, v0
	v_mov_b32_e32 v122, v0
	v_mov_b32_e32 v123, v0
	v_mov_b32_e32 v124, v0
	v_mov_b32_e32 v125, v0
	v_mov_b32_e32 v126, v0
	v_mov_b32_e32 v127, v0
	v_readfirstlane_b32 s98, v171
	s_add_i32 s35, s34, 0xfffe8000
	s_and_b32 s35, s35, 0x18000
	v_add_u32_e32 v235, s35, v168
	v_add_u32_e32 v236, s35, v170
	s_waitcnt vmcnt(8)
	s_barrier
	ds_read_b128 v[184:187], v235
	ds_read_b128 v[188:191], v235 offset:1024
	ds_read_b128 v[156:159], v236 offset:16384
	ds_read_b128 v[172:175], v236 offset:17408
	ds_read_b128 v[176:179], v236 offset:18432
	ds_read_b128 v[180:183], v236 offset:19456
	ds_read_b128 v[192:195], v235 offset:2048
	ds_read_b128 v[198:201], v235 offset:3072
	s_branch .Lp2a_mid
.Lp2a_top:
	s_add_i32 s35, s34, 0xfffe8000
	s_and_b32 s35, s35, 0x18000
	v_add_u32_e32 v235, s35, v168
	v_add_u32_e32 v236, s35, v170
	s_waitcnt vmcnt(8)
	s_barrier
	ds_read_b128 v[184:187], v235
	ds_read_b128 v[188:191], v235 offset:1024
	v_mfma_f32_16x16x32_bf16 v[28:31], v[192:195], v[156:159], v[28:31]
	v_mfma_f32_16x16x32_bf16 v[12:15], v[198:201], v[156:159], v[12:15]
	ds_read_b128 v[156:159], v236 offset:16384
	v_mfma_f32_16x16x32_bf16 v[24:27], v[192:195], v[172:175], v[24:27]
	v_mfma_f32_16x16x32_bf16 v[8:11], v[198:201], v[172:175], v[8:11]
	ds_read_b128 v[172:175], v236 offset:17408
	v_mfma_f32_16x16x32_bf16 v[20:23], v[192:195], v[176:179], v[20:23]
	v_mfma_f32_16x16x32_bf16 v[4:7], v[198:201], v[176:179], v[4:7]
	ds_read_b128 v[176:179], v236 offset:18432
	v_mfma_f32_16x16x32_bf16 v[16:19], v[192:195], v[180:183], v[16:19]
	v_mfma_f32_16x16x32_bf16 v[0:3], v[198:201], v[180:183], v[0:3]
	ds_read_b128 v[180:183], v236 offset:19456
	ds_read_b128 v[192:195], v235 offset:2048
	ds_read_b128 v[198:201], v235 offset:3072
; #define GEMM_WAITV(n) asm volatile("s_waitcnt vmcnt(" #n ")" ::: "memory")
; template <bool SWAP>
; __device__ __forceinline__ void gemm_main(f32x4 (&acc)[8][4], const TP& t, int nk, char* lds) {
;     ...
; #pragma unroll 1
;   for (int kt = 0; kt < nk - 3; ++kt) {
;     GEMM_WAITV(8);
;     GEMM_STEP(kt, true)
;   }
.Lp2a_mid:
	s_and_b32 s35, s34, 0x18000
	s_add_i32 s35, s35, s98
	s_mov_b32 m0, s35
	s_waitcnt lgkmcnt(5)
	v_mfma_f32_16x16x32_bf16 v[124:127], v[184:187], v[156:159], v[124:127]
	global_load_lds_dwordx4 v[136:137], off
	s_waitcnt lgkmcnt(4)
	v_mfma_f32_16x16x32_bf16 v[120:123], v[184:187], v[172:175], v[120:123]
	s_waitcnt lgkmcnt(3)
	v_mfma_f32_16x16x32_bf16 v[116:119], v[184:187], v[176:179], v[116:119]
	s_waitcnt lgkmcnt(2)
	v_mfma_f32_16x16x32_bf16 v[112:115], v[184:187], v[180:183], v[112:115]
	v_mfma_f32_16x16x32_bf16 v[108:111], v[188:191], v[156:159], v[108:111]
	v_mfma_f32_16x16x32_bf16 v[104:107], v[188:191], v[172:175], v[104:107]
	v_mfma_f32_16x16x32_bf16 v[100:103], v[188:191], v[176:179], v[100:103]
	v_mfma_f32_16x16x32_bf16 v[96:99], v[188:191], v[180:183], v[96:99]
	ds_read_b128 v[184:187], v235 offset:4096
	ds_read_b128 v[188:191], v235 offset:5120
	s_add_i32 m0, s35, 0x400
	s_waitcnt lgkmcnt(3)
	v_mfma_f32_16x16x32_bf16 v[92:95], v[192:195], v[156:159], v[92:95]
	global_load_lds_dwordx4 v[138:139], off
	v_mfma_f32_16x16x32_bf16 v[88:91], v[192:195], v[172:175], v[88:91]
	v_mfma_f32_16x16x32_bf16 v[84:87], v[192:195], v[176:179], v[84:87]
	v_mfma_f32_16x16x32_bf16 v[80:83], v[192:195], v[180:183], v[80:83]
	s_waitcnt lgkmcnt(2)
	v_mfma_f32_16x16x32_bf16 v[76:79], v[198:201], v[156:159], v[76:79]
	v_mfma_f32_16x16x32_bf16 v[72:75], v[198:201], v[172:175], v[72:75]
	v_mfma_f32_16x16x32_bf16 v[68:71], v[198:201], v[176:179], v[68:71]
	v_mfma_f32_16x16x32_bf16 v[64:67], v[198:201], v[180:183], v[64:67]
	ds_read_b128 v[192:195], v235 offset:6144
	ds_read_b128 v[198:201], v235 offset:7168
	s_add_i32 m0, s35, 0x4000
	s_waitcnt lgkmcnt(3)
	v_mfma_f32_16x16x32_bf16 v[60:63], v[184:187], v[156:159], v[60:63]
	global_load_lds_dwordx4 v[140:141], off
	v_mfma_f32_16x16x32_bf16 v[56:59], v[184:187], v[172:175], v[56:59]
	v_mfma_f32_16x16x32_bf16 v[52:55], v[184:187], v[176:179], v[52:55]
	v_mfma_f32_16x16x32_bf16 v[48:51], v[184:187], v[180:183], v[48:51]
	s_add_i32 m0, s35, 0x4400
	s_waitcnt lgkmcnt(2)
	v_mfma_f32_16x16x32_bf16 v[44:47], v[188:191], v[156:159], v[44:47]
	global_load_lds_dwordx4 v[142:143], off
	v_mfma_f32_16x16x32_bf16 v[40:43], v[188:191], v[172:175], v[40:43]
	v_lshl_add_u64 v[136:137], v[136:137], 0, 64
	v_lshl_add_u64 v[138:139], v[138:139], 0, 64
	v_lshl_add_u64 v[140:141], v[140:141], 0, 64
	v_lshl_add_u64 v[142:143], v[142:143], 0, 64
	s_add_i32 s34, s34, 0x8000
	v_mfma_f32_16x16x32_bf16 v[36:39], v[188:191], v[176:179], v[36:39]
	v_mfma_f32_16x16x32_bf16 v[32:35], v[188:191], v[180:183], v[32:35]
	s_waitcnt lgkmcnt(0)
	s_cmp_lg_u32 s34, 0x100000
	s_cbranch_scc1 .Lp2a_top
	v_add_u32_e32 v235, 0x8000, v168
	v_add_u32_e32 v236, 0x8000, v170
	s_waitcnt vmcnt(8)
	s_barrier
	ds_read_b128 v[184:187], v235
	ds_read_b128 v[188:191], v235 offset:1024
	v_mfma_f32_16x16x32_bf16 v[28:31], v[192:195], v[156:159], v[28:31]
	v_mfma_f32_16x16x32_bf16 v[12:15], v[198:201], v[156:159], v[12:15]
	ds_read_b128 v[156:159], v236 offset:16384
	v_mfma_f32_16x16x32_bf16 v[24:27], v[192:195], v[172:175], v[24:27]
	v_mfma_f32_16x16x32_bf16 v[8:11], v[198:201], v[172:175], v[8:11]
	ds_read_b128 v[172:175], v236 offset:17408
	v_mfma_f32_16x16x32_bf16 v[20:23], v[192:195], v[176:179], v[20:23]
	v_mfma_f32_16x16x32_bf16 v[4:7], v[198:201], v[176:179], v[4:7]
	ds_read_b128 v[176:179], v236 offset:18432
	v_mfma_f32_16x16x32_bf16 v[16:19], v[192:195], v[180:183], v[16:19]
	v_mfma_f32_16x16x32_bf16 v[0:3], v[198:201], v[180:183], v[0:3]
	ds_read_b128 v[180:183], v236 offset:19456
	ds_read_b128 v[192:195], v235 offset:2048
	ds_read_b128 v[198:201], v235 offset:3072
	s_waitcnt lgkmcnt(5)
	v_mfma_f32_16x16x32_bf16 v[124:127], v[184:187], v[156:159], v[124:127]
	s_waitcnt lgkmcnt(4)
	v_mfma_f32_16x16x32_bf16 v[120:123], v[184:187], v[172:175], v[120:123]
	s_waitcnt lgkmcnt(3)
	v_mfma_f32_16x16x32_bf16 v[116:119], v[184:187], v[176:179], v[116:119]
	s_waitcnt lgkmcnt(2)
	v_mfma_f32_16x16x32_bf16 v[112:115], v[184:187], v[180:183], v[112:115]
	v_mfma_f32_16x16x32_bf16 v[108:111], v[188:191], v[156:159], v[108:111]
	v_mfma_f32_16x16x32_bf16 v[104:107], v[188:191], v[172:175], v[104:107]
	v_mfma_f32_16x16x32_bf16 v[100:103], v[188:191], v[176:179], v[100:103]
	v_mfma_f32_16x16x32_bf16 v[96:99], v[188:191], v[180:183], v[96:99]
	ds_read_b128 v[184:187], v235 offset:4096
	ds_read_b128 v[188:191], v235 offset:5120
	s_waitcnt lgkmcnt(3)
	v_mfma_f32_16x16x32_bf16 v[92:95], v[192:195], v[156:159], v[92:95]
	v_mfma_f32_16x16x32_bf16 v[88:91], v[192:195], v[172:175], v[88:91]
	v_mfma_f32_16x16x32_bf16 v[84:87], v[192:195], v[176:179], v[84:87]
	v_mfma_f32_16x16x32_bf16 v[80:83], v[192:195], v[180:183], v[80:83]
	s_waitcnt lgkmcnt(2)
	v_mfma_f32_16x16x32_bf16 v[76:79], v[198:201], v[156:159], v[76:79]
	v_mfma_f32_16x16x32_bf16 v[72:75], v[198:201], v[172:175], v[72:75]
	v_mfma_f32_16x16x32_bf16 v[68:71], v[198:201], v[176:179], v[68:71]
	v_mfma_f32_16x16x32_bf16 v[64:67], v[198:201], v[180:183], v[64:67]
	ds_read_b128 v[192:195], v235 offset:6144
	ds_read_b128 v[198:201], v235 offset:7168
	s_waitcnt lgkmcnt(3)
	v_mfma_f32_16x16x32_bf16 v[60:63], v[184:187], v[156:159], v[60:63]
	v_mfma_f32_16x16x32_bf16 v[56:59], v[184:187], v[172:175], v[56:59]
	v_mfma_f32_16x16x32_bf16 v[52:55], v[184:187], v[176:179], v[52:55]
	v_mfma_f32_16x16x32_bf16 v[48:51], v[184:187], v[180:183], v[48:51]
	s_waitcnt lgkmcnt(2)
	v_mfma_f32_16x16x32_bf16 v[44:47], v[188:191], v[156:159], v[44:47]
	v_mfma_f32_16x16x32_bf16 v[40:43], v[188:191], v[172:175], v[40:43]
	v_mfma_f32_16x16x32_bf16 v[36:39], v[188:191], v[176:179], v[36:39]
	v_mfma_f32_16x16x32_bf16 v[32:35], v[188:191], v[180:183], v[32:35]
	s_waitcnt lgkmcnt(0)
	v_add_u32_e32 v235, 0x10000, v168
	v_add_u32_e32 v236, 0x10000, v170
	s_waitcnt vmcnt(4)
	s_barrier
; #define GEMM_WAITV(n) asm volatile("s_waitcnt vmcnt(" #n ")" ::: "memory")
; template <bool SWAP>
; __device__ __forceinline__ void gemm_main(f32x4 (&acc)[8][4], const TP& t, int nk, char* lds) {
;     ...
; #pragma unroll 1
;   for (int kt = 0; kt < nk - 3; ++kt) {
;     GEMM_WAITV(8);
;     GEMM_STEP(kt, true)
;   }
; #pragma unroll 1
;   for (int kt = nk - 3; kt < nk; ++kt) {
;     const int rem = nk - kt;
;     if (rem == 3) GEMM_WAITV(8); else if (rem == 2) GEMM_WAITV(4); else GEMM_WAITV(0);
;     GEMM_STEP(kt, false)
;   }
;   __builtin_amdgcn_s_barrier();
	ds_read_b128 v[184:187], v235
	ds_read_b128 v[188:191], v235 offset:1024
	v_mfma_f32_16x16x32_bf16 v[28:31], v[192:195], v[156:159], v[28:31]
	v_mfma_f32_16x16x32_bf16 v[12:15], v[198:201], v[156:159], v[12:15]
	ds_read_b128 v[156:159], v236 offset:16384
	v_mfma_f32_16x16x32_bf16 v[24:27], v[192:195], v[172:175], v[24:27]
	v_mfma_f32_16x16x32_bf16 v[8:11], v[198:201], v[172:175], v[8:11]
	ds_read_b128 v[172:175], v236 offset:17408
	v_mfma_f32_16x16x32_bf16 v[20:23], v[192:195], v[176:179], v[20:23]
	v_mfma_f32_16x16x32_bf16 v[4:7], v[198:201], v[176:179], v[4:7]
	ds_read_b128 v[176:179], v236 offset:18432
	v_mfma_f32_16x16x32_bf16 v[16:19], v[192:195], v[180:183], v[16:19]
	v_mfma_f32_16x16x32_bf16 v[0:3], v[198:201], v[180:183], v[0:3]
	ds_read_b128 v[180:183], v236 offset:19456
	ds_read_b128 v[192:195], v235 offset:2048
	ds_read_b128 v[198:201], v235 offset:3072
	s_waitcnt lgkmcnt(5)
	v_mfma_f32_16x16x32_bf16 v[124:127], v[184:187], v[156:159], v[124:127]
	s_waitcnt lgkmcnt(4)
	v_mfma_f32_16x16x32_bf16 v[120:123], v[184:187], v[172:175], v[120:123]
	s_waitcnt lgkmcnt(3)
	v_mfma_f32_16x16x32_bf16 v[116:119], v[184:187], v[176:179], v[116:119]
	s_waitcnt lgkmcnt(2)
	v_mfma_f32_16x16x32_bf16 v[112:115], v[184:187], v[180:183], v[112:115]
	v_mfma_f32_16x16x32_bf16 v[108:111], v[188:191], v[156:159], v[108:111]
	v_mfma_f32_16x16x32_bf16 v[104:107], v[188:191], v[172:175], v[104:107]
	v_mfma_f32_16x16x32_bf16 v[100:103], v[188:191], v[176:179], v[100:103]
	v_mfma_f32_16x16x32_bf16 v[96:99], v[188:191], v[180:183], v[96:99]
	ds_read_b128 v[184:187], v235 offset:4096
	ds_read_b128 v[188:191], v235 offset:5120
	s_waitcnt lgkmcnt(3)
	v_mfma_f32_16x16x32_bf16 v[92:95], v[192:195], v[156:159], v[92:95]
	v_mfma_f32_16x16x32_bf16 v[88:91], v[192:195], v[172:175], v[88:91]
	v_mfma_f32_16x16x32_bf16 v[84:87], v[192:195], v[176:179], v[84:87]
	v_mfma_f32_16x16x32_bf16 v[80:83], v[192:195], v[180:183], v[80:83]
	s_waitcnt lgkmcnt(2)
	v_mfma_f32_16x16x32_bf16 v[76:79], v[198:201], v[156:159], v[76:79]
	v_mfma_f32_16x16x32_bf16 v[72:75], v[198:201], v[172:175], v[72:75]
	v_mfma_f32_16x16x32_bf16 v[68:71], v[198:201], v[176:179], v[68:71]
	v_mfma_f32_16x16x32_bf16 v[64:67], v[198:201], v[180:183], v[64:67]
	ds_read_b128 v[192:195], v235 offset:6144
	ds_read_b128 v[198:201], v235 offset:7168
	s_waitcnt lgkmcnt(3)
	v_mfma_f32_16x16x32_bf16 v[60:63], v[184:187], v[156:159], v[60:63]
	v_mfma_f32_16x16x32_bf16 v[56:59], v[184:187], v[172:175], v[56:59]
	v_mfma_f32_16x16x32_bf16 v[52:55], v[184:187], v[176:179], v[52:55]
	v_mfma_f32_16x16x32_bf16 v[48:51], v[184:187], v[180:183], v[48:51]
	s_waitcnt lgkmcnt(2)
	v_mfma_f32_16x16x32_bf16 v[44:47], v[188:191], v[156:159], v[44:47]
	v_mfma_f32_16x16x32_bf16 v[40:43], v[188:191], v[172:175], v[40:43]
	v_mfma_f32_16x16x32_bf16 v[36:39], v[188:191], v[176:179], v[36:39]
	v_mfma_f32_16x16x32_bf16 v[32:35], v[188:191], v[180:183], v[32:35]
	s_waitcnt lgkmcnt(0)
	v_add_u32_e32 v235, 0x18000, v168
	v_add_u32_e32 v236, 0x18000, v170
	s_waitcnt vmcnt(0)
	s_barrier
	ds_read_b128 v[184:187], v235
	ds_read_b128 v[188:191], v235 offset:1024
	v_mfma_f32_16x16x32_bf16 v[28:31], v[192:195], v[156:159], v[28:31]
	v_mfma_f32_16x16x32_bf16 v[12:15], v[198:201], v[156:159], v[12:15]
	ds_read_b128 v[156:159], v236 offset:16384
	v_mfma_f32_16x16x32_bf16 v[24:27], v[192:195], v[172:175], v[24:27]
	v_mfma_f32_16x16x32_bf16 v[8:11], v[198:201], v[172:175], v[8:11]
	ds_read_b128 v[172:175], v236 offset:17408
	v_mfma_f32_16x16x32_bf16 v[20:23], v[192:195], v[176:179], v[20:23]
	v_mfma_f32_16x16x32_bf16 v[4:7], v[198:201], v[176:179], v[4:7]
	ds_read_b128 v[176:179], v236 offset:18432
	v_mfma_f32_16x16x32_bf16 v[16:19], v[192:195], v[180:183], v[16:19]
	v_mfma_f32_16x16x32_bf16 v[0:3], v[198:201], v[180:183], v[0:3]
	ds_read_b128 v[180:183], v236 offset:19456
	ds_read_b128 v[192:195], v235 offset:2048
	ds_read_b128 v[198:201], v235 offset:3072
	s_waitcnt lgkmcnt(5)
	v_mfma_f32_16x16x32_bf16 v[124:127], v[184:187], v[156:159], v[124:127]
	s_waitcnt lgkmcnt(4)
	v_mfma_f32_16x16x32_bf16 v[120:123], v[184:187], v[172:175], v[120:123]
	s_waitcnt lgkmcnt(3)
	v_mfma_f32_16x16x32_bf16 v[116:119], v[184:187], v[176:179], v[116:119]
	s_waitcnt lgkmcnt(2)
	v_mfma_f32_16x16x32_bf16 v[112:115], v[184:187], v[180:183], v[112:115]
	v_mfma_f32_16x16x32_bf16 v[108:111], v[188:191], v[156:159], v[108:111]
	v_mfma_f32_16x16x32_bf16 v[104:107], v[188:191], v[172:175], v[104:107]
	v_mfma_f32_16x16x32_bf16 v[100:103], v[188:191], v[176:179], v[100:103]
	v_mfma_f32_16x16x32_bf16 v[96:99], v[188:191], v[180:183], v[96:99]
	ds_read_b128 v[184:187], v235 offset:4096
	ds_read_b128 v[188:191], v235 offset:5120
	s_waitcnt lgkmcnt(3)
	v_mfma_f32_16x16x32_bf16 v[92:95], v[192:195], v[156:159], v[92:95]
	v_mfma_f32_16x16x32_bf16 v[88:91], v[192:195], v[172:175], v[88:91]
	v_mfma_f32_16x16x32_bf16 v[84:87], v[192:195], v[176:179], v[84:87]
	v_mfma_f32_16x16x32_bf16 v[80:83], v[192:195], v[180:183], v[80:83]
	s_waitcnt lgkmcnt(2)
	v_mfma_f32_16x16x32_bf16 v[76:79], v[198:201], v[156:159], v[76:79]
	v_mfma_f32_16x16x32_bf16 v[72:75], v[198:201], v[172:175], v[72:75]
	v_mfma_f32_16x16x32_bf16 v[68:71], v[198:201], v[176:179], v[68:71]
	v_mfma_f32_16x16x32_bf16 v[64:67], v[198:201], v[180:183], v[64:67]
	ds_read_b128 v[192:195], v235 offset:6144
	ds_read_b128 v[198:201], v235 offset:7168
	s_waitcnt lgkmcnt(3)
	v_mfma_f32_16x16x32_bf16 v[60:63], v[184:187], v[156:159], v[60:63]
	v_mfma_f32_16x16x32_bf16 v[56:59], v[184:187], v[172:175], v[56:59]
	v_mfma_f32_16x16x32_bf16 v[52:55], v[184:187], v[176:179], v[52:55]
	v_mfma_f32_16x16x32_bf16 v[48:51], v[184:187], v[180:183], v[48:51]
	s_waitcnt lgkmcnt(2)
	v_mfma_f32_16x16x32_bf16 v[44:47], v[188:191], v[156:159], v[44:47]
	v_mfma_f32_16x16x32_bf16 v[40:43], v[188:191], v[172:175], v[40:43]
	v_mfma_f32_16x16x32_bf16 v[36:39], v[188:191], v[176:179], v[36:39]
	v_mfma_f32_16x16x32_bf16 v[32:35], v[188:191], v[180:183], v[32:35]
	s_waitcnt lgkmcnt(0)
	v_mfma_f32_16x16x32_bf16 v[28:31], v[192:195], v[156:159], v[28:31]
	v_mfma_f32_16x16x32_bf16 v[12:15], v[198:201], v[156:159], v[12:15]
	v_mfma_f32_16x16x32_bf16 v[24:27], v[192:195], v[172:175], v[24:27]
	v_mfma_f32_16x16x32_bf16 v[8:11], v[198:201], v[172:175], v[8:11]
	v_mfma_f32_16x16x32_bf16 v[20:23], v[192:195], v[176:179], v[20:23]
	v_mfma_f32_16x16x32_bf16 v[4:7], v[198:201], v[176:179], v[4:7]
	v_mfma_f32_16x16x32_bf16 v[16:19], v[192:195], v[180:183], v[16:19]
	v_mfma_f32_16x16x32_bf16 v[0:3], v[198:201], v[180:183], v[0:3]
	s_nop 7

; template <class MK, class SW, class EPI>
; __device__ __forceinline__ void gemm_phase(int first, int step, int n, int nk, MK mk, SW swapf, EPI epi, char* lds) {
;     ...
;     if (swapf(it)) gemm_main<true>(acc, cur, nk, lds); else gemm_main<false>(acc, cur, nk, lds);
; __device__ __forceinline__ void zero_acc(f32x4 (&acc)[8][4]) {
; #pragma unroll
;   for (int i = 0; i < 8; ++i)
; #pragma unroll
;     for (int j = 0; j < 4; ++j) acc[i][j] = (f32x4){0.f, 0.f, 0.f, 0.f};
.LBB0_401:
	s_and_b64 vcc, exec, s[34:35]
	s_cbranch_vccz .LBB0_417
	s_nop 2
	v_mov_b32_e32 v0, v153
	s_mov_b32 s34, 0x18000
	v_lshlrev_b32_e32 v3, 2, v0
	v_and_b32_e32 v3, 48, v3
	v_sub_u32_e32 v3, 0, v3
	v_and_b32_e32 v136, 15, v0
	v_lshlrev_b32_e32 v1, 5, v0
	v_lshlrev_b32_e32 v2, 4, v0
	v_bitop3_b32 v137, v0, 48, v3 bitop3:0x48
	v_ashrrev_i32_e32 v138, 1, v0
	v_lshlrev_b32_e32 v0, 6, v0
	v_and_b32_e32 v1, 0xfffff800, v1
	v_and_b32_e32 v2, 0x3f0, v2
	v_and_or_b32 v3, v138, s41, v136
	v_and_b32_e32 v139, 0x33c0, v0
	v_mov_b32_e32 v0, 0
	v_lshl_or_b32 v140, v3, 6, v137
	v_or_b32_e32 v141, v139, v137
	v_add3_u32 v142, 0, v1, v2
	v_mov_b32_e32 v1, v0
	v_mov_b32_e32 v2, v0
	v_mov_b32_e32 v3, v0
	v_mov_b32_e32 v4, v0
	v_mov_b32_e32 v5, v0
	v_mov_b32_e32 v6, v0
	v_mov_b32_e32 v7, v0
	v_mov_b32_e32 v8, v0
	v_mov_b32_e32 v9, v0
	v_mov_b32_e32 v10, v0
	v_mov_b32_e32 v11, v0
	v_mov_b32_e32 v12, v0
	v_mov_b32_e32 v13, v0
	v_mov_b32_e32 v14, v0
	v_mov_b32_e32 v15, v0
	v_mov_b32_e32 v16, v0
	v_mov_b32_e32 v17, v0
	v_mov_b32_e32 v18, v0
	v_mov_b32_e32 v19, v0
	v_mov_b32_e32 v20, v0
	v_mov_b32_e32 v21, v0
	v_mov_b32_e32 v22, v0
	v_mov_b32_e32 v23, v0
	v_mov_b32_e32 v24, v0
	v_mov_b32_e32 v25, v0
	v_mov_b32_e32 v26, v0
	v_mov_b32_e32 v27, v0
	v_mov_b32_e32 v28, v0
	v_mov_b32_e32 v29, v0
	v_mov_b32_e32 v30, v0
	v_mov_b32_e32 v31, v0
	v_mov_b32_e32 v32, v0
	v_mov_b32_e32 v33, v0
	v_mov_b32_e32 v34, v0
	v_mov_b32_e32 v35, v0
	v_mov_b32_e32 v36, v0
	v_mov_b32_e32 v37, v0
	v_mov_b32_e32 v38, v0
	v_mov_b32_e32 v39, v0
	v_mov_b32_e32 v40, v0
	v_mov_b32_e32 v41, v0
	v_mov_b32_e32 v42, v0
	v_mov_b32_e32 v43, v0
	v_mov_b32_e32 v44, v0
	v_mov_b32_e32 v45, v0
	v_mov_b32_e32 v46, v0
	v_mov_b32_e32 v47, v0
	v_mov_b32_e32 v48, v0
	v_mov_b32_e32 v49, v0
	v_mov_b32_e32 v50, v0
	v_mov_b32_e32 v51, v0
	v_mov_b32_e32 v52, v0
	v_mov_b32_e32 v53, v0
	v_mov_b32_e32 v54, v0
	v_mov_b32_e32 v55, v0
	v_mov_b32_e32 v56, v0
	v_mov_b32_e32 v57, v0
	v_mov_b32_e32 v58, v0
	v_mov_b32_e32 v59, v0
	v_mov_b32_e32 v60, v0
	v_mov_b32_e32 v61, v0
	v_mov_b32_e32 v62, v0
	v_mov_b32_e32 v63, v0
	v_mov_b32_e32 v64, v0
	v_mov_b32_e32 v65, v0
	v_mov_b32_e32 v66, v0
	v_mov_b32_e32 v67, v0
	v_mov_b32_e32 v68, v0
	v_mov_b32_e32 v69, v0
	v_mov_b32_e32 v70, v0
	v_mov_b32_e32 v71, v0
	v_mov_b32_e32 v72, v0
	v_mov_b32_e32 v73, v0
	v_mov_b32_e32 v74, v0
	v_mov_b32_e32 v75, v0
	v_mov_b32_e32 v76, v0
	v_mov_b32_e32 v77, v0
	v_mov_b32_e32 v78, v0
	v_mov_b32_e32 v79, v0
	v_mov_b32_e32 v80, v0
	v_mov_b32_e32 v81, v0
	v_mov_b32_e32 v82, v0
	v_mov_b32_e32 v83, v0
	v_mov_b32_e32 v84, v0
	v_mov_b32_e32 v85, v0
	v_mov_b32_e32 v86, v0
	v_mov_b32_e32 v87, v0
	v_mov_b32_e32 v88, v0
	v_mov_b32_e32 v89, v0
	v_mov_b32_e32 v90, v0
	v_mov_b32_e32 v91, v0
	v_mov_b32_e32 v92, v0
	v_mov_b32_e32 v93, v0
	v_mov_b32_e32 v94, v0
	v_mov_b32_e32 v95, v0
	v_mov_b32_e32 v96, v0
	v_mov_b32_e32 v97, v0
	v_mov_b32_e32 v98, v0
	v_mov_b32_e32 v99, v0
	v_mov_b32_e32 v100, v0
	v_mov_b32_e32 v101, v0
	v_mov_b32_e32 v102, v0
	v_mov_b32_e32 v103, v0
	v_mov_b32_e32 v104, v0
	v_mov_b32_e32 v105, v0
	v_mov_b32_e32 v106, v0
	v_mov_b32_e32 v107, v0
	v_mov_b32_e32 v108, v0
	v_mov_b32_e32 v109, v0
	v_mov_b32_e32 v110, v0
	v_mov_b32_e32 v111, v0
	v_mov_b32_e32 v112, v0
	v_mov_b32_e32 v113, v0
	v_mov_b32_e32 v114, v0
	v_mov_b32_e32 v115, v0
	v_mov_b32_e32 v116, v0
	v_mov_b32_e32 v117, v0
	v_mov_b32_e32 v118, v0
	v_mov_b32_e32 v119, v0
	v_mov_b32_e32 v120, v0
	v_mov_b32_e32 v121, v0
	v_mov_b32_e32 v122, v0
	v_mov_b32_e32 v123, v0
	v_mov_b32_e32 v124, v0
	v_mov_b32_e32 v125, v0
	v_mov_b32_e32 v126, v0
	v_mov_b32_e32 v127, v0
	v_readfirstlane_b32 s98, v142
	s_add_i32 s35, s34, 0xfffe8000
	s_and_b32 s35, s35, 0x18000
	v_add_u32_e32 v235, s35, v140
	v_add_u32_e32 v236, s35, v141
	s_waitcnt vmcnt(8)
	s_barrier
	ds_read_b128 v[178:181], v235
	ds_read_b128 v[182:185], v235 offset:1024
	ds_read_b128 v[156:159], v236 offset:16384
	ds_read_b128 v[164:167], v236 offset:17408
	ds_read_b128 v[170:173], v236 offset:18432
	ds_read_b128 v[174:177], v236 offset:19456
	ds_read_b128 v[186:189], v235 offset:2048
	ds_read_b128 v[190:193], v235 offset:3072
	s_branch .Lp2b_mid
.Lp2b_top:
	s_add_i32 s35, s34, 0xfffe8000
	s_and_b32 s35, s35, 0x18000
	v_add_u32_e32 v235, s35, v140
	v_add_u32_e32 v236, s35, v141
	s_waitcnt vmcnt(8)
	s_barrier
	ds_read_b128 v[178:181], v235
	ds_read_b128 v[182:185], v235 offset:1024
	v_mfma_f32_16x16x32_bf16 v[28:31], v[156:159], v[186:189], v[28:31]
	v_mfma_f32_16x16x32_bf16 v[12:15], v[156:159], v[190:193], v[12:15]
	ds_read_b128 v[156:159], v236 offset:16384
	v_mfma_f32_16x16x32_bf16 v[24:27], v[164:167], v[186:189], v[24:27]
	v_mfma_f32_16x16x32_bf16 v[8:11], v[164:167], v[190:193], v[8:11]
	ds_read_b128 v[164:167], v236 offset:17408
	v_mfma_f32_16x16x32_bf16 v[20:23], v[170:173], v[186:189], v[20:23]
	v_mfma_f32_16x16x32_bf16 v[4:7], v[170:173], v[190:193], v[4:7]
	ds_read_b128 v[170:173], v236 offset:18432
	v_mfma_f32_16x16x32_bf16 v[16:19], v[174:177], v[186:189], v[16:19]
	v_mfma_f32_16x16x32_bf16 v[0:3], v[174:177], v[190:193], v[0:3]
	ds_read_b128 v[174:177], v236 offset:19456
	ds_read_b128 v[186:189], v235 offset:2048
	ds_read_b128 v[190:193], v235 offset:3072
; #define GEMM_WAITV(n) asm volatile("s_waitcnt vmcnt(" #n ")" ::: "memory")
; template <bool SWAP>
; __device__ __forceinline__ void gemm_main(f32x4 (&acc)[8][4], const TP& t, int nk, char* lds) {
;     ...
; #pragma unroll 1
;   for (int kt = 0; kt < nk - 3; ++kt) {
;     GEMM_WAITV(8);
;     GEMM_STEP(kt, true)
;   }
.Lp2b_mid:
	s_and_b32 s35, s34, 0x18000
	s_add_i32 s35, s35, s98
	s_mov_b32 m0, s35
	s_waitcnt lgkmcnt(5)
	v_mfma_f32_16x16x32_bf16 v[124:127], v[156:159], v[178:181], v[124:127]
	global_load_lds_dwordx4 v[128:129], off
	s_waitcnt lgkmcnt(4)
	v_mfma_f32_16x16x32_bf16 v[120:123], v[164:167], v[178:181], v[120:123]
	s_waitcnt lgkmcnt(3)
	v_mfma_f32_16x16x32_bf16 v[116:119], v[170:173], v[178:181], v[116:119]
	s_waitcnt lgkmcnt(2)
	v_mfma_f32_16x16x32_bf16 v[112:115], v[174:177], v[178:181], v[112:115]
	v_mfma_f32_16x16x32_bf16 v[108:111], v[156:159], v[182:185], v[108:111]
	v_mfma_f32_16x16x32_bf16 v[104:107], v[164:167], v[182:185], v[104:107]
	v_mfma_f32_16x16x32_bf16 v[100:103], v[170:173], v[182:185], v[100:103]
	v_mfma_f32_16x16x32_bf16 v[96:99], v[174:177], v[182:185], v[96:99]
	ds_read_b128 v[178:181], v235 offset:4096
	ds_read_b128 v[182:185], v235 offset:5120
	s_add_i32 m0, s35, 0x400
	s_waitcnt lgkmcnt(3)
	v_mfma_f32_16x16x32_bf16 v[92:95], v[156:159], v[186:189], v[92:95]
	global_load_lds_dwordx4 v[130:131], off
	v_mfma_f32_16x16x32_bf16 v[88:91], v[164:167], v[186:189], v[88:91]
	v_mfma_f32_16x16x32_bf16 v[84:87], v[170:173], v[186:189], v[84:87]
	v_mfma_f32_16x16x32_bf16 v[80:83], v[174:177], v[186:189], v[80:83]
	s_waitcnt lgkmcnt(2)
	v_mfma_f32_16x16x32_bf16 v[76:79], v[156:159], v[190:193], v[76:79]
	v_mfma_f32_16x16x32_bf16 v[72:75], v[164:167], v[190:193], v[72:75]
	v_mfma_f32_16x16x32_bf16 v[68:71], v[170:173], v[190:193], v[68:71]
	v_mfma_f32_16x16x32_bf16 v[64:67], v[174:177], v[190:193], v[64:67]
	ds_read_b128 v[186:189], v235 offset:6144
	ds_read_b128 v[190:193], v235 offset:7168
	s_add_i32 m0, s35, 0x4000
	s_waitcnt lgkmcnt(3)
	v_mfma_f32_16x16x32_bf16 v[60:63], v[156:159], v[178:181], v[60:63]
	global_load_lds_dwordx4 v[132:133], off
	v_mfma_f32_16x16x32_bf16 v[56:59], v[164:167], v[178:181], v[56:59]
	v_mfma_f32_16x16x32_bf16 v[52:55], v[170:173], v[178:181], v[52:55]
	v_mfma_f32_16x16x32_bf16 v[48:51], v[174:177], v[178:181], v[48:51]
	s_add_i32 m0, s35, 0x4400
	s_waitcnt lgkmcnt(2)
	v_mfma_f32_16x16x32_bf16 v[44:47], v[156:159], v[182:185], v[44:47]
	global_load_lds_dwordx4 v[134:135], off
	v_mfma_f32_16x16x32_bf16 v[40:43], v[164:167], v[182:185], v[40:43]
	v_lshl_add_u64 v[128:129], v[128:129], 0, 64
	v_lshl_add_u64 v[130:131], v[130:131], 0, 64
	v_lshl_add_u64 v[132:133], v[132:133], 0, 64
	v_lshl_add_u64 v[134:135], v[134:135], 0, 64
	s_add_i32 s34, s34, 0x8000
	v_mfma_f32_16x16x32_bf16 v[36:39], v[170:173], v[182:185], v[36:39]
	v_mfma_f32_16x16x32_bf16 v[32:35], v[174:177], v[182:185], v[32:35]
	s_waitcnt lgkmcnt(0)
	s_cmp_lg_u32 s34, 0x100000
	s_cbranch_scc1 .Lp2b_top
	v_add_u32_e32 v235, 0x8000, v140
	v_add_u32_e32 v236, 0x8000, v141
	s_waitcnt vmcnt(8)
	s_barrier
	ds_read_b128 v[178:181], v235
	ds_read_b128 v[182:185], v235 offset:1024
	v_mfma_f32_16x16x32_bf16 v[28:31], v[156:159], v[186:189], v[28:31]
	v_mfma_f32_16x16x32_bf16 v[12:15], v[156:159], v[190:193], v[12:15]
	ds_read_b128 v[156:159], v236 offset:16384
	v_mfma_f32_16x16x32_bf16 v[24:27], v[164:167], v[186:189], v[24:27]
	v_mfma_f32_16x16x32_bf16 v[8:11], v[164:167], v[190:193], v[8:11]
	ds_read_b128 v[164:167], v236 offset:17408
	v_mfma_f32_16x16x32_bf16 v[20:23], v[170:173], v[186:189], v[20:23]
	v_mfma_f32_16x16x32_bf16 v[4:7], v[170:173], v[190:193], v[4:7]
	ds_read_b128 v[170:173], v236 offset:18432
	v_mfma_f32_16x16x32_bf16 v[16:19], v[174:177], v[186:189], v[16:19]
	v_mfma_f32_16x16x32_bf16 v[0:3], v[174:177], v[190:193], v[0:3]
	ds_read_b128 v[174:177], v236 offset:19456
	ds_read_b128 v[186:189], v235 offset:2048
	ds_read_b128 v[190:193], v235 offset:3072
	s_waitcnt lgkmcnt(5)
	v_mfma_f32_16x16x32_bf16 v[124:127], v[156:159], v[178:181], v[124:127]
	s_waitcnt lgkmcnt(4)
	v_mfma_f32_16x16x32_bf16 v[120:123], v[164:167], v[178:181], v[120:123]
	s_waitcnt lgkmcnt(3)
	v_mfma_f32_16x16x32_bf16 v[116:119], v[170:173], v[178:181], v[116:119]
	s_waitcnt lgkmcnt(2)
	v_mfma_f32_16x16x32_bf16 v[112:115], v[174:177], v[178:181], v[112:115]
	v_mfma_f32_16x16x32_bf16 v[108:111], v[156:159], v[182:185], v[108:111]
	v_mfma_f32_16x16x32_bf16 v[104:107], v[164:167], v[182:185], v[104:107]
	v_mfma_f32_16x16x32_bf16 v[100:103], v[170:173], v[182:185], v[100:103]
	v_mfma_f32_16x16x32_bf16 v[96:99], v[174:177], v[182:185], v[96:99]
	ds_read_b128 v[178:181], v235 offset:4096
	ds_read_b128 v[182:185], v235 offset:5120
	s_waitcnt lgkmcnt(3)
	v_mfma_f32_16x16x32_bf16 v[92:95], v[156:159], v[186:189], v[92:95]
	v_mfma_f32_16x16x32_bf16 v[88:91], v[164:167], v[186:189], v[88:91]
	v_mfma_f32_16x16x32_bf16 v[84:87], v[170:173], v[186:189], v[84:87]
	v_mfma_f32_16x16x32_bf16 v[80:83], v[174:177], v[186:189], v[80:83]
	s_waitcnt lgkmcnt(2)
	v_mfma_f32_16x16x32_bf16 v[76:79], v[156:159], v[190:193], v[76:79]
	v_mfma_f32_16x16x32_bf16 v[72:75], v[164:167], v[190:193], v[72:75]
	v_mfma_f32_16x16x32_bf16 v[68:71], v[170:173], v[190:193], v[68:71]
	v_mfma_f32_16x16x32_bf16 v[64:67], v[174:177], v[190:193], v[64:67]
	ds_read_b128 v[186:189], v235 offset:6144
	ds_read_b128 v[190:193], v235 offset:7168
	s_waitcnt lgkmcnt(3)
	v_mfma_f32_16x16x32_bf16 v[60:63], v[156:159], v[178:181], v[60:63]
	v_mfma_f32_16x16x32_bf16 v[56:59], v[164:167], v[178:181], v[56:59]
	v_mfma_f32_16x16x32_bf16 v[52:55], v[170:173], v[178:181], v[52:55]
	v_mfma_f32_16x16x32_bf16 v[48:51], v[174:177], v[178:181], v[48:51]
	s_waitcnt lgkmcnt(2)
	v_mfma_f32_16x16x32_bf16 v[44:47], v[156:159], v[182:185], v[44:47]
	v_mfma_f32_16x16x32_bf16 v[40:43], v[164:167], v[182:185], v[40:43]
	v_mfma_f32_16x16x32_bf16 v[36:39], v[170:173], v[182:185], v[36:39]
	v_mfma_f32_16x16x32_bf16 v[32:35], v[174:177], v[182:185], v[32:35]
	s_waitcnt lgkmcnt(0)
	v_add_u32_e32 v235, 0x10000, v140
	v_add_u32_e32 v236, 0x10000, v141
	s_waitcnt vmcnt(4)
	s_barrier
; #define GEMM_WAITV(n) asm volatile("s_waitcnt vmcnt(" #n ")" ::: "memory")
; template <bool SWAP>
; __device__ __forceinline__ void gemm_main(f32x4 (&acc)[8][4], const TP& t, int nk, char* lds) {
;     ...
; #pragma unroll 1
;   for (int kt = 0; kt < nk - 3; ++kt) {
;     GEMM_WAITV(8);
;     GEMM_STEP(kt, true)
;   }
; #pragma unroll 1
;   for (int kt = nk - 3; kt < nk; ++kt) {
;     const int rem = nk - kt;
;     if (rem == 3) GEMM_WAITV(8); else if (rem == 2) GEMM_WAITV(4); else GEMM_WAITV(0);
;     GEMM_STEP(kt, false)
;   }
;   __builtin_amdgcn_s_barrier();
	ds_read_b128 v[178:181], v235
	ds_read_b128 v[182:185], v235 offset:1024
	v_mfma_f32_16x16x32_bf16 v[28:31], v[156:159], v[186:189], v[28:31]
	v_mfma_f32_16x16x32_bf16 v[12:15], v[156:159], v[190:193], v[12:15]
	ds_read_b128 v[156:159], v236 offset:16384
	v_mfma_f32_16x16x32_bf16 v[24:27], v[164:167], v[186:189], v[24:27]
	v_mfma_f32_16x16x32_bf16 v[8:11], v[164:167], v[190:193], v[8:11]
	ds_read_b128 v[164:167], v236 offset:17408
	v_mfma_f32_16x16x32_bf16 v[20:23], v[170:173], v[186:189], v[20:23]
	v_mfma_f32_16x16x32_bf16 v[4:7], v[170:173], v[190:193], v[4:7]
	ds_read_b128 v[170:173], v236 offset:18432
	v_mfma_f32_16x16x32_bf16 v[16:19], v[174:177], v[186:189], v[16:19]
	v_mfma_f32_16x16x32_bf16 v[0:3], v[174:177], v[190:193], v[0:3]
	ds_read_b128 v[174:177], v236 offset:19456
	ds_read_b128 v[186:189], v235 offset:2048
	ds_read_b128 v[190:193], v235 offset:3072
	s_waitcnt lgkmcnt(5)
	v_mfma_f32_16x16x32_bf16 v[124:127], v[156:159], v[178:181], v[124:127]
	s_waitcnt lgkmcnt(4)
	v_mfma_f32_16x16x32_bf16 v[120:123], v[164:167], v[178:181], v[120:123]
	s_waitcnt lgkmcnt(3)
	v_mfma_f32_16x16x32_bf16 v[116:119], v[170:173], v[178:181], v[116:119]
	s_waitcnt lgkmcnt(2)
	v_mfma_f32_16x16x32_bf16 v[112:115], v[174:177], v[178:181], v[112:115]
	v_mfma_f32_16x16x32_bf16 v[108:111], v[156:159], v[182:185], v[108:111]
	v_mfma_f32_16x16x32_bf16 v[104:107], v[164:167], v[182:185], v[104:107]
	v_mfma_f32_16x16x32_bf16 v[100:103], v[170:173], v[182:185], v[100:103]
	v_mfma_f32_16x16x32_bf16 v[96:99], v[174:177], v[182:185], v[96:99]
	ds_read_b128 v[178:181], v235 offset:4096
	ds_read_b128 v[182:185], v235 offset:5120
	s_waitcnt lgkmcnt(3)
	v_mfma_f32_16x16x32_bf16 v[92:95], v[156:159], v[186:189], v[92:95]
	v_mfma_f32_16x16x32_bf16 v[88:91], v[164:167], v[186:189], v[88:91]
	v_mfma_f32_16x16x32_bf16 v[84:87], v[170:173], v[186:189], v[84:87]
	v_mfma_f32_16x16x32_bf16 v[80:83], v[174:177], v[186:189], v[80:83]
	s_waitcnt lgkmcnt(2)
	v_mfma_f32_16x16x32_bf16 v[76:79], v[156:159], v[190:193], v[76:79]
	v_mfma_f32_16x16x32_bf16 v[72:75], v[164:167], v[190:193], v[72:75]
	v_mfma_f32_16x16x32_bf16 v[68:71], v[170:173], v[190:193], v[68:71]
	v_mfma_f32_16x16x32_bf16 v[64:67], v[174:177], v[190:193], v[64:67]
	ds_read_b128 v[186:189], v235 offset:6144
	ds_read_b128 v[190:193], v235 offset:7168
	s_waitcnt lgkmcnt(3)
	v_mfma_f32_16x16x32_bf16 v[60:63], v[156:159], v[178:181], v[60:63]
	v_mfma_f32_16x16x32_bf16 v[56:59], v[164:167], v[178:181], v[56:59]
	v_mfma_f32_16x16x32_bf16 v[52:55], v[170:173], v[178:181], v[52:55]
	v_mfma_f32_16x16x32_bf16 v[48:51], v[174:177], v[178:181], v[48:51]
	s_waitcnt lgkmcnt(2)
	v_mfma_f32_16x16x32_bf16 v[44:47], v[156:159], v[182:185], v[44:47]
	v_mfma_f32_16x16x32_bf16 v[40:43], v[164:167], v[182:185], v[40:43]
	v_mfma_f32_16x16x32_bf16 v[36:39], v[170:173], v[182:185], v[36:39]
	v_mfma_f32_16x16x32_bf16 v[32:35], v[174:177], v[182:185], v[32:35]
	s_waitcnt lgkmcnt(0)
	v_add_u32_e32 v235, 0x18000, v140
	v_add_u32_e32 v236, 0x18000, v141
	s_waitcnt vmcnt(0)
	s_barrier
	ds_read_b128 v[178:181], v235
	ds_read_b128 v[182:185], v235 offset:1024
	v_mfma_f32_16x16x32_bf16 v[28:31], v[156:159], v[186:189], v[28:31]
	v_mfma_f32_16x16x32_bf16 v[12:15], v[156:159], v[190:193], v[12:15]
	ds_read_b128 v[156:159], v236 offset:16384
	v_mfma_f32_16x16x32_bf16 v[24:27], v[164:167], v[186:189], v[24:27]
	v_mfma_f32_16x16x32_bf16 v[8:11], v[164:167], v[190:193], v[8:11]
	ds_read_b128 v[164:167], v236 offset:17408
	v_mfma_f32_16x16x32_bf16 v[20:23], v[170:173], v[186:189], v[20:23]
	v_mfma_f32_16x16x32_bf16 v[4:7], v[170:173], v[190:193], v[4:7]
	ds_read_b128 v[170:173], v236 offset:18432
	v_mfma_f32_16x16x32_bf16 v[16:19], v[174:177], v[186:189], v[16:19]
	v_mfma_f32_16x16x32_bf16 v[0:3], v[174:177], v[190:193], v[0:3]
	ds_read_b128 v[174:177], v236 offset:19456
	ds_read_b128 v[186:189], v235 offset:2048
	ds_read_b128 v[190:193], v235 offset:3072
	s_waitcnt lgkmcnt(5)
	v_mfma_f32_16x16x32_bf16 v[124:127], v[156:159], v[178:181], v[124:127]
	s_waitcnt lgkmcnt(4)
	v_mfma_f32_16x16x32_bf16 v[120:123], v[164:167], v[178:181], v[120:123]
	s_waitcnt lgkmcnt(3)
	v_mfma_f32_16x16x32_bf16 v[116:119], v[170:173], v[178:181], v[116:119]
	s_waitcnt lgkmcnt(2)
	v_mfma_f32_16x16x32_bf16 v[112:115], v[174:177], v[178:181], v[112:115]
	v_mfma_f32_16x16x32_bf16 v[108:111], v[156:159], v[182:185], v[108:111]
	v_mfma_f32_16x16x32_bf16 v[104:107], v[164:167], v[182:185], v[104:107]
	v_mfma_f32_16x16x32_bf16 v[100:103], v[170:173], v[182:185], v[100:103]
	v_mfma_f32_16x16x32_bf16 v[96:99], v[174:177], v[182:185], v[96:99]
	ds_read_b128 v[178:181], v235 offset:4096
	ds_read_b128 v[182:185], v235 offset:5120
	s_waitcnt lgkmcnt(3)
	v_mfma_f32_16x16x32_bf16 v[92:95], v[156:159], v[186:189], v[92:95]
	v_mfma_f32_16x16x32_bf16 v[88:91], v[164:167], v[186:189], v[88:91]
	v_mfma_f32_16x16x32_bf16 v[84:87], v[170:173], v[186:189], v[84:87]
	v_mfma_f32_16x16x32_bf16 v[80:83], v[174:177], v[186:189], v[80:83]
	s_waitcnt lgkmcnt(2)
	v_mfma_f32_16x16x32_bf16 v[76:79], v[156:159], v[190:193], v[76:79]
	v_mfma_f32_16x16x32_bf16 v[72:75], v[164:167], v[190:193], v[72:75]
	v_mfma_f32_16x16x32_bf16 v[68:71], v[170:173], v[190:193], v[68:71]
	v_mfma_f32_16x16x32_bf16 v[64:67], v[174:177], v[190:193], v[64:67]
	ds_read_b128 v[186:189], v235 offset:6144
	ds_read_b128 v[190:193], v235 offset:7168
	s_waitcnt lgkmcnt(3)
	v_mfma_f32_16x16x32_bf16 v[60:63], v[156:159], v[178:181], v[60:63]
	v_mfma_f32_16x16x32_bf16 v[56:59], v[164:167], v[178:181], v[56:59]
	v_mfma_f32_16x16x32_bf16 v[52:55], v[170:173], v[178:181], v[52:55]
	v_mfma_f32_16x16x32_bf16 v[48:51], v[174:177], v[178:181], v[48:51]
	s_waitcnt lgkmcnt(2)
	v_mfma_f32_16x16x32_bf16 v[44:47], v[156:159], v[182:185], v[44:47]
	v_mfma_f32_16x16x32_bf16 v[40:43], v[164:167], v[182:185], v[40:43]
	v_mfma_f32_16x16x32_bf16 v[36:39], v[170:173], v[182:185], v[36:39]
	v_mfma_f32_16x16x32_bf16 v[32:35], v[174:177], v[182:185], v[32:35]
	s_waitcnt lgkmcnt(0)
	v_mfma_f32_16x16x32_bf16 v[28:31], v[156:159], v[186:189], v[28:31]
	v_mfma_f32_16x16x32_bf16 v[12:15], v[156:159], v[190:193], v[12:15]
	v_mfma_f32_16x16x32_bf16 v[24:27], v[164:167], v[186:189], v[24:27]
	v_mfma_f32_16x16x32_bf16 v[8:11], v[164:167], v[190:193], v[8:11]
	v_mfma_f32_16x16x32_bf16 v[20:23], v[170:173], v[186:189], v[20:23]
	v_mfma_f32_16x16x32_bf16 v[4:7], v[170:173], v[190:193], v[4:7]
	v_mfma_f32_16x16x32_bf16 v[16:19], v[174:177], v[186:189], v[16:19]
	v_mfma_f32_16x16x32_bf16 v[0:3], v[174:177], v[190:193], v[0:3]
	s_nop 7

; __device__ __forceinline__ void zero_acc(f32x4 (&acc)[8][4]) {
; #pragma unroll
;   for (int i = 0; i < 8; ++i)
; #pragma unroll
;     for (int j = 0; j < 4; ++j) acc[i][j] = (f32x4){0.f, 0.f, 0.f, 0.f};
; __device__ __forceinline__ void merge_phase(const Params& p, int first, int step, int n, char* lds) {
;     ...
;   TP cur = merge_ptrs(p, first >> 2, first & 3, 0);
;   gemm_issue3(cur, lds);
; #pragma unroll 1
;   for (int it = first; it < n; it += step) {
;     const int mt = it >> 2, nt = it & 3;
;     f32x4 acc[8][4];
;     zero_acc(acc);
;     gemm_main<true>(acc, cur, 16, lds);
.LBB0_845:
	v_mov_b32_e32 v0, v153
	v_mov_b32_e32 v8, 0
	v_lshlrev_b32_e32 v3, 2, v0
	v_and_b32_e32 v3, 48, v3
	v_sub_u32_e32 v3, 0, v3
	v_and_b32_e32 v136, 15, v0
	v_lshlrev_b32_e32 v1, 5, v0
	v_lshlrev_b32_e32 v2, 4, v0
	v_bitop3_b32 v137, v0, 48, v3 bitop3:0x48
	v_ashrrev_i32_e32 v138, 1, v0
	v_lshlrev_b32_e32 v0, 6, v0
	v_and_b32_e32 v1, 0xfffff800, v1
	v_and_b32_e32 v2, 0x3f0, v2
	v_and_or_b32 v3, v138, s68, v136
	v_and_b32_e32 v139, 0x33c0, v0
	v_lshl_or_b32 v140, v3, 6, v137
	v_or_b32_e32 v141, v139, v137
	v_add3_u32 v142, 0, v1, v2
	v_lshl_add_u64 v[128:129], v[158:159], 0, s[40:41]
	v_lshl_add_u64 v[130:131], v[162:163], 0, s[40:41]
	v_lshl_add_u64 v[132:133], v[160:161], 0, s[40:41]
	v_lshl_add_u64 v[134:135], v[164:165], 0, s[40:41]
	s_mov_b32 s46, 0x18000
	v_mov_b32_e32 v9, v8
	v_mov_b32_e32 v10, v8
	v_mov_b32_e32 v11, v8
	v_mov_b32_e32 v24, v8
	v_mov_b32_e32 v25, v8
	v_mov_b32_e32 v26, v8
	v_mov_b32_e32 v27, v8
	v_mov_b32_e32 v32, v8
	v_mov_b32_e32 v33, v8
	v_mov_b32_e32 v34, v8
	v_mov_b32_e32 v35, v8
	v_mov_b32_e32 v36, v8
	v_mov_b32_e32 v37, v8
	v_mov_b32_e32 v38, v8
	v_mov_b32_e32 v39, v8
	v_mov_b32_e32 v44, v8
	v_mov_b32_e32 v45, v8
	v_mov_b32_e32 v46, v8
	v_mov_b32_e32 v47, v8
	v_mov_b32_e32 v60, v8
	v_mov_b32_e32 v61, v8
	v_mov_b32_e32 v62, v8
	v_mov_b32_e32 v63, v8
	v_mov_b32_e32 v64, v8
	v_mov_b32_e32 v65, v8
	v_mov_b32_e32 v66, v8
	v_mov_b32_e32 v67, v8
	v_mov_b32_e32 v84, v8
	v_mov_b32_e32 v85, v8
	v_mov_b32_e32 v86, v8
	v_mov_b32_e32 v87, v8
	v_mov_b32_e32 v88, v8
	v_mov_b32_e32 v89, v8
	v_mov_b32_e32 v90, v8
	v_mov_b32_e32 v91, v8
	v_mov_b32_e32 v92, v8
	v_mov_b32_e32 v93, v8
	v_mov_b32_e32 v94, v8
	v_mov_b32_e32 v95, v8
	v_mov_b32_e32 v112, v8
	v_mov_b32_e32 v113, v8
	v_mov_b32_e32 v114, v8
	v_mov_b32_e32 v115, v8
	v_mov_b32_e32 v124, v8
	v_mov_b32_e32 v125, v8
	v_mov_b32_e32 v126, v8
	v_mov_b32_e32 v127, v8
	v_mov_b32_e32 v116, v8
	v_mov_b32_e32 v117, v8
	v_mov_b32_e32 v118, v8
	v_mov_b32_e32 v119, v8
	v_mov_b32_e32 v120, v8
	v_mov_b32_e32 v121, v8
	v_mov_b32_e32 v122, v8
	v_mov_b32_e32 v123, v8
	v_mov_b32_e32 v108, v8
	v_mov_b32_e32 v109, v8
	v_mov_b32_e32 v110, v8
	v_mov_b32_e32 v111, v8
	v_mov_b32_e32 v104, v8
	v_mov_b32_e32 v105, v8
	v_mov_b32_e32 v106, v8
	v_mov_b32_e32 v107, v8
	v_mov_b32_e32 v96, v8
	v_mov_b32_e32 v97, v8
	v_mov_b32_e32 v98, v8
	v_mov_b32_e32 v99, v8
	v_mov_b32_e32 v100, v8
	v_mov_b32_e32 v101, v8
	v_mov_b32_e32 v102, v8
	v_mov_b32_e32 v103, v8
	v_mov_b32_e32 v80, v8
	v_mov_b32_e32 v81, v8
	v_mov_b32_e32 v82, v8
	v_mov_b32_e32 v83, v8
	v_mov_b32_e32 v76, v8
	v_mov_b32_e32 v77, v8
	v_mov_b32_e32 v78, v8
	v_mov_b32_e32 v79, v8
	v_mov_b32_e32 v68, v8
	v_mov_b32_e32 v69, v8
	v_mov_b32_e32 v70, v8
	v_mov_b32_e32 v71, v8
	v_mov_b32_e32 v72, v8
	v_mov_b32_e32 v73, v8
	v_mov_b32_e32 v74, v8
	v_mov_b32_e32 v75, v8
	v_mov_b32_e32 v56, v8
	v_mov_b32_e32 v57, v8
	v_mov_b32_e32 v58, v8
	v_mov_b32_e32 v59, v8
	v_mov_b32_e32 v52, v8
	v_mov_b32_e32 v53, v8
	v_mov_b32_e32 v54, v8
	v_mov_b32_e32 v55, v8
	v_mov_b32_e32 v40, v8
	v_mov_b32_e32 v41, v8
	v_mov_b32_e32 v42, v8
	v_mov_b32_e32 v43, v8
	v_mov_b32_e32 v48, v8
	v_mov_b32_e32 v49, v8
	v_mov_b32_e32 v50, v8
	v_mov_b32_e32 v51, v8
	v_mov_b32_e32 v28, v8
	v_mov_b32_e32 v29, v8
	v_mov_b32_e32 v30, v8
	v_mov_b32_e32 v31, v8
	v_mov_b32_e32 v20, v8
	v_mov_b32_e32 v21, v8
	v_mov_b32_e32 v22, v8
	v_mov_b32_e32 v23, v8
	v_mov_b32_e32 v12, v8
	v_mov_b32_e32 v13, v8
	v_mov_b32_e32 v14, v8
	v_mov_b32_e32 v15, v8
	v_mov_b32_e32 v16, v8
	v_mov_b32_e32 v17, v8
	v_mov_b32_e32 v18, v8
	v_mov_b32_e32 v19, v8
	v_mov_b32_e32 v4, v8
	v_mov_b32_e32 v5, v8
	v_mov_b32_e32 v6, v8
	v_mov_b32_e32 v7, v8
	v_mov_b32_e32 v0, v8
	v_mov_b32_e32 v1, v8
	v_mov_b32_e32 v2, v8
	v_mov_b32_e32 v3, v8
	v_readfirstlane_b32 s98, v142
	s_add_i32 s47, s46, 0xfffe8000
	s_and_b32 s47, s47, 0x18000
	v_add_u32_e32 v235, s47, v140
	v_add_u32_e32 v236, s47, v141
	s_waitcnt vmcnt(8)
	s_barrier
	ds_read_b128 v[174:177], v235
	ds_read_b128 v[178:181], v235 offset:1024
	ds_read_b128 v[144:147], v236 offset:16384
	ds_read_b128 v[158:161], v236 offset:17408
	ds_read_b128 v[162:165], v236 offset:18432
	ds_read_b128 v[170:173], v236 offset:19456
	ds_read_b128 v[182:185], v235 offset:2048
	ds_read_b128 v[186:189], v235 offset:3072
	s_branch .Lmg1_mid
.Lmg1_top:
	s_add_i32 s47, s46, 0xfffe8000
	s_and_b32 s47, s47, 0x18000
	v_add_u32_e32 v235, s47, v140
	v_add_u32_e32 v236, s47, v141
	s_waitcnt vmcnt(8)
	s_barrier
	ds_read_b128 v[174:177], v235
	ds_read_b128 v[178:181], v235 offset:1024
	v_mfma_f32_16x16x32_bf16 v[84:87], v[144:147], v[182:185], v[84:87]
	v_mfma_f32_16x16x32_bf16 v[36:39], v[144:147], v[186:189], v[36:39]
	ds_read_b128 v[144:147], v236 offset:16384
	v_mfma_f32_16x16x32_bf16 v[64:67], v[158:161], v[182:185], v[64:67]
	v_mfma_f32_16x16x32_bf16 v[32:35], v[158:161], v[186:189], v[32:35]
	ds_read_b128 v[158:161], v236 offset:17408
	v_mfma_f32_16x16x32_bf16 v[60:63], v[162:165], v[182:185], v[60:63]
	v_mfma_f32_16x16x32_bf16 v[24:27], v[162:165], v[186:189], v[24:27]
	ds_read_b128 v[162:165], v236 offset:18432
	v_mfma_f32_16x16x32_bf16 v[44:47], v[170:173], v[182:185], v[44:47]
	v_mfma_f32_16x16x32_bf16 v[8:11], v[170:173], v[186:189], v[8:11]
	ds_read_b128 v[170:173], v236 offset:19456
	ds_read_b128 v[182:185], v235 offset:2048
	ds_read_b128 v[186:189], v235 offset:3072
; #define GEMM_WAITV(n) asm volatile("s_waitcnt vmcnt(" #n ")" ::: "memory")
; template <bool SWAP>
; __device__ __forceinline__ void gemm_main(f32x4 (&acc)[8][4], const TP& t, int nk, char* lds) {
;     ...
; #pragma unroll 1
;   for (int kt = 0; kt < nk - 3; ++kt) {
;     GEMM_WAITV(8);
;     GEMM_STEP(kt, true)
;   }
.Lmg1_mid:
	s_and_b32 s47, s46, 0x18000
	s_add_i32 s47, s47, s98
	s_mov_b32 m0, s47
	s_waitcnt lgkmcnt(5)
	v_mfma_f32_16x16x32_bf16 v[0:3], v[144:147], v[174:177], v[0:3]
	global_load_lds_dwordx4 v[128:129], off
	s_waitcnt lgkmcnt(4)
	v_mfma_f32_16x16x32_bf16 v[4:7], v[158:161], v[174:177], v[4:7]
	s_waitcnt lgkmcnt(3)
	v_mfma_f32_16x16x32_bf16 v[16:19], v[162:165], v[174:177], v[16:19]
	s_waitcnt lgkmcnt(2)
	v_mfma_f32_16x16x32_bf16 v[12:15], v[170:173], v[174:177], v[12:15]
	v_mfma_f32_16x16x32_bf16 v[20:23], v[144:147], v[178:181], v[20:23]
	v_mfma_f32_16x16x32_bf16 v[28:31], v[158:161], v[178:181], v[28:31]
	v_mfma_f32_16x16x32_bf16 v[48:51], v[162:165], v[178:181], v[48:51]
	v_mfma_f32_16x16x32_bf16 v[40:43], v[170:173], v[178:181], v[40:43]
	ds_read_b128 v[174:177], v235 offset:4096
	ds_read_b128 v[178:181], v235 offset:5120
	s_add_i32 m0, s47, 0x400
	s_waitcnt lgkmcnt(3)
	v_mfma_f32_16x16x32_bf16 v[52:55], v[144:147], v[182:185], v[52:55]
	global_load_lds_dwordx4 v[130:131], off
	v_mfma_f32_16x16x32_bf16 v[56:59], v[158:161], v[182:185], v[56:59]
	v_mfma_f32_16x16x32_bf16 v[72:75], v[162:165], v[182:185], v[72:75]
	v_mfma_f32_16x16x32_bf16 v[68:71], v[170:173], v[182:185], v[68:71]
	s_waitcnt lgkmcnt(2)
	v_mfma_f32_16x16x32_bf16 v[76:79], v[144:147], v[186:189], v[76:79]
	v_mfma_f32_16x16x32_bf16 v[80:83], v[158:161], v[186:189], v[80:83]
	v_mfma_f32_16x16x32_bf16 v[100:103], v[162:165], v[186:189], v[100:103]
	v_mfma_f32_16x16x32_bf16 v[96:99], v[170:173], v[186:189], v[96:99]
	ds_read_b128 v[182:185], v235 offset:6144
	ds_read_b128 v[186:189], v235 offset:7168
	s_add_i32 m0, s47, 0x4000
	s_waitcnt lgkmcnt(3)
	v_mfma_f32_16x16x32_bf16 v[104:107], v[144:147], v[174:177], v[104:107]
	global_load_lds_dwordx4 v[132:133], off
	v_mfma_f32_16x16x32_bf16 v[108:111], v[158:161], v[174:177], v[108:111]
	v_mfma_f32_16x16x32_bf16 v[120:123], v[162:165], v[174:177], v[120:123]
	v_mfma_f32_16x16x32_bf16 v[116:119], v[170:173], v[174:177], v[116:119]
	s_add_i32 m0, s47, 0x4400
	s_waitcnt lgkmcnt(2)
	v_mfma_f32_16x16x32_bf16 v[124:127], v[144:147], v[178:181], v[124:127]
	global_load_lds_dwordx4 v[134:135], off
	v_mfma_f32_16x16x32_bf16 v[112:115], v[158:161], v[178:181], v[112:115]
	v_lshl_add_u64 v[128:129], v[128:129], 0, 64
	v_lshl_add_u64 v[130:131], v[130:131], 0, 64
	v_lshl_add_u64 v[132:133], v[132:133], 0, 64
	v_lshl_add_u64 v[134:135], v[134:135], 0, 64
	s_add_i32 s46, s46, 0x8000
	v_mfma_f32_16x16x32_bf16 v[92:95], v[162:165], v[178:181], v[92:95]
	v_mfma_f32_16x16x32_bf16 v[88:91], v[170:173], v[178:181], v[88:91]
	s_waitcnt lgkmcnt(0)
	s_cmp_lg_u32 s46, 0x80000
	s_cbranch_scc1 .Lmg1_top
	v_add_u32_e32 v235, 0x8000, v140
	v_add_u32_e32 v236, 0x8000, v141
	s_waitcnt vmcnt(8)
	s_barrier
	ds_read_b128 v[174:177], v235
	ds_read_b128 v[178:181], v235 offset:1024
	v_mfma_f32_16x16x32_bf16 v[84:87], v[144:147], v[182:185], v[84:87]
	v_mfma_f32_16x16x32_bf16 v[36:39], v[144:147], v[186:189], v[36:39]
	ds_read_b128 v[144:147], v236 offset:16384
	v_mfma_f32_16x16x32_bf16 v[64:67], v[158:161], v[182:185], v[64:67]
	v_mfma_f32_16x16x32_bf16 v[32:35], v[158:161], v[186:189], v[32:35]
	ds_read_b128 v[158:161], v236 offset:17408
	v_mfma_f32_16x16x32_bf16 v[60:63], v[162:165], v[182:185], v[60:63]
	v_mfma_f32_16x16x32_bf16 v[24:27], v[162:165], v[186:189], v[24:27]
	ds_read_b128 v[162:165], v236 offset:18432
	v_mfma_f32_16x16x32_bf16 v[44:47], v[170:173], v[182:185], v[44:47]
	v_mfma_f32_16x16x32_bf16 v[8:11], v[170:173], v[186:189], v[8:11]
	ds_read_b128 v[170:173], v236 offset:19456
	ds_read_b128 v[182:185], v235 offset:2048
	ds_read_b128 v[186:189], v235 offset:3072
	s_waitcnt lgkmcnt(5)
	v_mfma_f32_16x16x32_bf16 v[0:3], v[144:147], v[174:177], v[0:3]
	s_waitcnt lgkmcnt(4)
	v_mfma_f32_16x16x32_bf16 v[4:7], v[158:161], v[174:177], v[4:7]
	s_waitcnt lgkmcnt(3)
	v_mfma_f32_16x16x32_bf16 v[16:19], v[162:165], v[174:177], v[16:19]
	s_waitcnt lgkmcnt(2)
	v_mfma_f32_16x16x32_bf16 v[12:15], v[170:173], v[174:177], v[12:15]
	v_mfma_f32_16x16x32_bf16 v[20:23], v[144:147], v[178:181], v[20:23]
	v_mfma_f32_16x16x32_bf16 v[28:31], v[158:161], v[178:181], v[28:31]
	v_mfma_f32_16x16x32_bf16 v[48:51], v[162:165], v[178:181], v[48:51]
	v_mfma_f32_16x16x32_bf16 v[40:43], v[170:173], v[178:181], v[40:43]
	ds_read_b128 v[174:177], v235 offset:4096
	ds_read_b128 v[178:181], v235 offset:5120
	s_waitcnt lgkmcnt(3)
	v_mfma_f32_16x16x32_bf16 v[52:55], v[144:147], v[182:185], v[52:55]
	v_mfma_f32_16x16x32_bf16 v[56:59], v[158:161], v[182:185], v[56:59]
	v_mfma_f32_16x16x32_bf16 v[72:75], v[162:165], v[182:185], v[72:75]
	v_mfma_f32_16x16x32_bf16 v[68:71], v[170:173], v[182:185], v[68:71]
	s_waitcnt lgkmcnt(2)
	v_mfma_f32_16x16x32_bf16 v[76:79], v[144:147], v[186:189], v[76:79]
	v_mfma_f32_16x16x32_bf16 v[80:83], v[158:161], v[186:189], v[80:83]
	v_mfma_f32_16x16x32_bf16 v[100:103], v[162:165], v[186:189], v[100:103]
	v_mfma_f32_16x16x32_bf16 v[96:99], v[170:173], v[186:189], v[96:99]
	ds_read_b128 v[182:185], v235 offset:6144
	ds_read_b128 v[186:189], v235 offset:7168
	s_waitcnt lgkmcnt(3)
	v_mfma_f32_16x16x32_bf16 v[104:107], v[144:147], v[174:177], v[104:107]
	v_mfma_f32_16x16x32_bf16 v[108:111], v[158:161], v[174:177], v[108:111]
	v_mfma_f32_16x16x32_bf16 v[120:123], v[162:165], v[174:177], v[120:123]
	v_mfma_f32_16x16x32_bf16 v[116:119], v[170:173], v[174:177], v[116:119]
	s_waitcnt lgkmcnt(2)
	v_mfma_f32_16x16x32_bf16 v[124:127], v[144:147], v[178:181], v[124:127]
	v_mfma_f32_16x16x32_bf16 v[112:115], v[158:161], v[178:181], v[112:115]
	v_mfma_f32_16x16x32_bf16 v[92:95], v[162:165], v[178:181], v[92:95]
	v_mfma_f32_16x16x32_bf16 v[88:91], v[170:173], v[178:181], v[88:91]
	s_waitcnt lgkmcnt(0)
	v_add_u32_e32 v235, 0x10000, v140
	v_add_u32_e32 v236, 0x10000, v141
	s_waitcnt vmcnt(4)
	s_barrier
; #define GEMM_WAITV(n) asm volatile("s_waitcnt vmcnt(" #n ")" ::: "memory")
; template <bool SWAP>
; __device__ __forceinline__ void gemm_main(f32x4 (&acc)[8][4], const TP& t, int nk, char* lds) {
;     ...
; #pragma unroll 1
;   for (int kt = 0; kt < nk - 3; ++kt) {
;     GEMM_WAITV(8);
;     GEMM_STEP(kt, true)
;   }
; #pragma unroll 1
;   for (int kt = nk - 3; kt < nk; ++kt) {
;     const int rem = nk - kt;
;     if (rem == 3) GEMM_WAITV(8); else if (rem == 2) GEMM_WAITV(4); else GEMM_WAITV(0);
;     GEMM_STEP(kt, false)
;   }
;   __builtin_amdgcn_s_barrier();
	ds_read_b128 v[174:177], v235
	ds_read_b128 v[178:181], v235 offset:1024
	v_mfma_f32_16x16x32_bf16 v[84:87], v[144:147], v[182:185], v[84:87]
	v_mfma_f32_16x16x32_bf16 v[36:39], v[144:147], v[186:189], v[36:39]
	ds_read_b128 v[144:147], v236 offset:16384
	v_mfma_f32_16x16x32_bf16 v[64:67], v[158:161], v[182:185], v[64:67]
	v_mfma_f32_16x16x32_bf16 v[32:35], v[158:161], v[186:189], v[32:35]
	ds_read_b128 v[158:161], v236 offset:17408
	v_mfma_f32_16x16x32_bf16 v[60:63], v[162:165], v[182:185], v[60:63]
	v_mfma_f32_16x16x32_bf16 v[24:27], v[162:165], v[186:189], v[24:27]
	ds_read_b128 v[162:165], v236 offset:18432
	v_mfma_f32_16x16x32_bf16 v[44:47], v[170:173], v[182:185], v[44:47]
	v_mfma_f32_16x16x32_bf16 v[8:11], v[170:173], v[186:189], v[8:11]
	ds_read_b128 v[170:173], v236 offset:19456
	ds_read_b128 v[182:185], v235 offset:2048
	ds_read_b128 v[186:189], v235 offset:3072
	s_waitcnt lgkmcnt(5)
	v_mfma_f32_16x16x32_bf16 v[0:3], v[144:147], v[174:177], v[0:3]
	s_waitcnt lgkmcnt(4)
	v_mfma_f32_16x16x32_bf16 v[4:7], v[158:161], v[174:177], v[4:7]
	s_waitcnt lgkmcnt(3)
	v_mfma_f32_16x16x32_bf16 v[16:19], v[162:165], v[174:177], v[16:19]
	s_waitcnt lgkmcnt(2)
	v_mfma_f32_16x16x32_bf16 v[12:15], v[170:173], v[174:177], v[12:15]
	v_mfma_f32_16x16x32_bf16 v[20:23], v[144:147], v[178:181], v[20:23]
	v_mfma_f32_16x16x32_bf16 v[28:31], v[158:161], v[178:181], v[28:31]
	v_mfma_f32_16x16x32_bf16 v[48:51], v[162:165], v[178:181], v[48:51]
	v_mfma_f32_16x16x32_bf16 v[40:43], v[170:173], v[178:181], v[40:43]
	ds_read_b128 v[174:177], v235 offset:4096
	ds_read_b128 v[178:181], v235 offset:5120
	s_waitcnt lgkmcnt(3)
	v_mfma_f32_16x16x32_bf16 v[52:55], v[144:147], v[182:185], v[52:55]
	v_mfma_f32_16x16x32_bf16 v[56:59], v[158:161], v[182:185], v[56:59]
	v_mfma_f32_16x16x32_bf16 v[72:75], v[162:165], v[182:185], v[72:75]
	v_mfma_f32_16x16x32_bf16 v[68:71], v[170:173], v[182:185], v[68:71]
	s_waitcnt lgkmcnt(2)
	v_mfma_f32_16x16x32_bf16 v[76:79], v[144:147], v[186:189], v[76:79]
	v_mfma_f32_16x16x32_bf16 v[80:83], v[158:161], v[186:189], v[80:83]
	v_mfma_f32_16x16x32_bf16 v[100:103], v[162:165], v[186:189], v[100:103]
	v_mfma_f32_16x16x32_bf16 v[96:99], v[170:173], v[186:189], v[96:99]
	ds_read_b128 v[182:185], v235 offset:6144
	ds_read_b128 v[186:189], v235 offset:7168
	s_waitcnt lgkmcnt(3)
	v_mfma_f32_16x16x32_bf16 v[104:107], v[144:147], v[174:177], v[104:107]
	v_mfma_f32_16x16x32_bf16 v[108:111], v[158:161], v[174:177], v[108:111]
	v_mfma_f32_16x16x32_bf16 v[120:123], v[162:165], v[174:177], v[120:123]
	v_mfma_f32_16x16x32_bf16 v[116:119], v[170:173], v[174:177], v[116:119]
	s_waitcnt lgkmcnt(2)
	v_mfma_f32_16x16x32_bf16 v[124:127], v[144:147], v[178:181], v[124:127]
	v_mfma_f32_16x16x32_bf16 v[112:115], v[158:161], v[178:181], v[112:115]
	v_mfma_f32_16x16x32_bf16 v[92:95], v[162:165], v[178:181], v[92:95]
	v_mfma_f32_16x16x32_bf16 v[88:91], v[170:173], v[178:181], v[88:91]
	s_waitcnt lgkmcnt(0)
	v_add_u32_e32 v235, 0x18000, v140
	v_add_u32_e32 v236, 0x18000, v141
	s_waitcnt vmcnt(0)
	s_barrier
	ds_read_b128 v[174:177], v235
	ds_read_b128 v[178:181], v235 offset:1024
	v_mfma_f32_16x16x32_bf16 v[84:87], v[144:147], v[182:185], v[84:87]
	v_mfma_f32_16x16x32_bf16 v[36:39], v[144:147], v[186:189], v[36:39]
	ds_read_b128 v[144:147], v236 offset:16384
	v_mfma_f32_16x16x32_bf16 v[64:67], v[158:161], v[182:185], v[64:67]
	v_mfma_f32_16x16x32_bf16 v[32:35], v[158:161], v[186:189], v[32:35]
	ds_read_b128 v[158:161], v236 offset:17408
	v_mfma_f32_16x16x32_bf16 v[60:63], v[162:165], v[182:185], v[60:63]
	v_mfma_f32_16x16x32_bf16 v[24:27], v[162:165], v[186:189], v[24:27]
	ds_read_b128 v[162:165], v236 offset:18432
	v_mfma_f32_16x16x32_bf16 v[44:47], v[170:173], v[182:185], v[44:47]
	v_mfma_f32_16x16x32_bf16 v[8:11], v[170:173], v[186:189], v[8:11]
	ds_read_b128 v[170:173], v236 offset:19456
	ds_read_b128 v[182:185], v235 offset:2048
	ds_read_b128 v[186:189], v235 offset:3072
	s_waitcnt lgkmcnt(5)
	v_mfma_f32_16x16x32_bf16 v[0:3], v[144:147], v[174:177], v[0:3]
	s_waitcnt lgkmcnt(4)
	v_mfma_f32_16x16x32_bf16 v[4:7], v[158:161], v[174:177], v[4:7]
	s_waitcnt lgkmcnt(3)
	v_mfma_f32_16x16x32_bf16 v[16:19], v[162:165], v[174:177], v[16:19]
	s_waitcnt lgkmcnt(2)
	v_mfma_f32_16x16x32_bf16 v[12:15], v[170:173], v[174:177], v[12:15]
	v_mfma_f32_16x16x32_bf16 v[20:23], v[144:147], v[178:181], v[20:23]
	v_mfma_f32_16x16x32_bf16 v[28:31], v[158:161], v[178:181], v[28:31]
	v_mfma_f32_16x16x32_bf16 v[48:51], v[162:165], v[178:181], v[48:51]
	v_mfma_f32_16x16x32_bf16 v[40:43], v[170:173], v[178:181], v[40:43]
	ds_read_b128 v[174:177], v235 offset:4096
	ds_read_b128 v[178:181], v235 offset:5120
	s_waitcnt lgkmcnt(3)
	v_mfma_f32_16x16x32_bf16 v[52:55], v[144:147], v[182:185], v[52:55]
	v_mfma_f32_16x16x32_bf16 v[56:59], v[158:161], v[182:185], v[56:59]
	v_mfma_f32_16x16x32_bf16 v[72:75], v[162:165], v[182:185], v[72:75]
	v_mfma_f32_16x16x32_bf16 v[68:71], v[170:173], v[182:185], v[68:71]
	s_waitcnt lgkmcnt(2)
	v_mfma_f32_16x16x32_bf16 v[76:79], v[144:147], v[186:189], v[76:79]
	v_mfma_f32_16x16x32_bf16 v[80:83], v[158:161], v[186:189], v[80:83]
	v_mfma_f32_16x16x32_bf16 v[100:103], v[162:165], v[186:189], v[100:103]
	v_mfma_f32_16x16x32_bf16 v[96:99], v[170:173], v[186:189], v[96:99]
	ds_read_b128 v[182:185], v235 offset:6144
	ds_read_b128 v[186:189], v235 offset:7168
	s_waitcnt lgkmcnt(3)
	v_mfma_f32_16x16x32_bf16 v[104:107], v[144:147], v[174:177], v[104:107]
	v_mfma_f32_16x16x32_bf16 v[108:111], v[158:161], v[174:177], v[108:111]
	v_mfma_f32_16x16x32_bf16 v[120:123], v[162:165], v[174:177], v[120:123]
	v_mfma_f32_16x16x32_bf16 v[116:119], v[170:173], v[174:177], v[116:119]
	s_waitcnt lgkmcnt(2)
	v_mfma_f32_16x16x32_bf16 v[124:127], v[144:147], v[178:181], v[124:127]
	v_mfma_f32_16x16x32_bf16 v[112:115], v[158:161], v[178:181], v[112:115]
	v_mfma_f32_16x16x32_bf16 v[92:95], v[162:165], v[178:181], v[92:95]
	v_mfma_f32_16x16x32_bf16 v[88:91], v[170:173], v[178:181], v[88:91]
	s_waitcnt lgkmcnt(0)
	v_mfma_f32_16x16x32_bf16 v[84:87], v[144:147], v[182:185], v[84:87]
	v_mfma_f32_16x16x32_bf16 v[36:39], v[144:147], v[186:189], v[36:39]
	v_mfma_f32_16x16x32_bf16 v[64:67], v[158:161], v[182:185], v[64:67]
	v_mfma_f32_16x16x32_bf16 v[32:35], v[158:161], v[186:189], v[32:35]
	v_mfma_f32_16x16x32_bf16 v[60:63], v[162:165], v[182:185], v[60:63]
	v_mfma_f32_16x16x32_bf16 v[24:27], v[162:165], v[186:189], v[24:27]
	v_mfma_f32_16x16x32_bf16 v[44:47], v[170:173], v[182:185], v[44:47]
	v_mfma_f32_16x16x32_bf16 v[8:11], v[170:173], v[186:189], v[8:11]
	s_nop 7
; __device__ __forceinline__ int otid() { int t = threadIdx.x; asm volatile("" : "+v"(t)); return t; }
; __device__ __forceinline__ int trow(int j) { const int t = otid(); return ((t >> 6) * 2 + j) * 16 + ((t & 63) >> 2); }
; __device__ __forceinline__ void gemm_issue3(const TP& t, char* lds) {
;   const int tid = otid();
;   const int ldoff = (tid >> 6) * 2048 + (tid & 63) * 16;
; #pragma unroll
;   for (int st = 0; st < 3; ++st) {
;     char* As = lds + st * T_STAGE + ldoff; char* Bs = As + T_ASTAGE;
;     glds16(t.a0 + st * 32, As); glds16(t.a1 + st * 32, As + 1024);
;     glds16(t.b0 + st * 32, Bs); glds16(t.b1 + st * 32, Bs + 1024);
;   }
; }
; __device__ __forceinline__ TP merge_ptrs(const Params& p, int mt, int nt, int br) {
;   TP t;
;   t.a0 = (const u16*)(p.ws + (br ? OFF_NA : OFF_HY)) + (size_t)(mt * 256 + trow(0)) * 512 + tkc(); t.a1 = t.a0 + 16 * 512;
;   t.b0 = (const u16*)(p.ws + (br ? OFF_WBN : OFF_WBH)) + (size_t)(nt * 256 + perm_row(trow(0))) * 512 + tkc();
;   t.b1 = (const u16*)(p.ws + (br ? OFF_WBN : OFF_WBH)) + (size_t)(nt * 256 + perm_row(trow(1))) * 512 + tkc();
;   return t;
; }
; __device__ __forceinline__ void merge_phase(const Params& p, int first, int step, int n, char* lds) {
;   if (first >= n) return;
;   const int tid = otid(), lane = tid & 63, wave = tid >> 6;
;   const int wm = wave >> 2, wn = wave & 3, lr = lane & 15, lq = lane >> 4;
;   const u16* gates = (const u16*)(p.ws + OFF_GATES);
;   u16* M = (u16*)(p.ws + OFF_ACT1);
;   asm volatile("s_waitcnt vmcnt(0)" ::: "memory");
;   TP cur = merge_ptrs(p, first >> 2, first & 3, 0);
;   gemm_issue3(cur, lds);
; #pragma unroll 1
;   for (int it = first; it < n; it += step) {
;     const int mt = it >> 2, nt = it & 3;
;     f32x4 acc[8][4];
;     zero_acc(acc);
;     gemm_main<true>(acc, cur, 16, lds);
;     cur = merge_ptrs(p, mt, nt, 1);
;     gemm_issue3(cur, lds);
; #pragma unroll
;     for (int i = 0; i < 8; ++i) {
;       const int m = mt * 256 + wm * 128 + i * 16 + lr;
;       const int n0 = nt * 256 + wn * 64 + lq * 16;
;       union { uint4 v[2]; u16 e[16]; } gh, gn;
;       gh.v[0] = *(const uint4*)(gates + (size_t)m * 2048 + n0); gh.v[1] = *(const uint4*)(gates + (size_t)m * 2048 + n0 + 8);
;       gn.v[0] = *(const uint4*)(gates + (size_t)m * 2048 + 1024 + n0); gn.v[1] = *(const uint4*)(gates + (size_t)m * 2048 + 1024 + n0 + 8);
.LBB0_859:
	s_lshl_b32 s54, s71, 6
	v_mov_b32_e32 v128, v153
	s_barrier
	s_and_b32 s54, s54, 0xffffff00
	v_mov_b32_e32 v199, v153
	v_ashrrev_i32_e32 v129, 1, v128
	v_bfe_u32 v198, v128, 2, 4
	v_and_b32_e32 v155, 0xffffffe0, v129
	v_or_b32_e32 v128, s54, v198
	v_add_u32_e32 v128, v128, v155
	v_lshrrev_b32_e32 v130, 4, v199
	v_sub_u32_e32 v200, 0, v130
	v_ashrrev_i32_e32 v129, 31, v128
	v_xor_b32_e32 v130, v199, v200
	v_lshlrev_b64 v[128:129], 10, v[128:129]
	v_lshlrev_b32_e32 v130, 4, v130
	v_lshl_add_u64 v[128:129], s[22:23], 0, v[128:129]
	v_and_b32_e32 v156, 48, v130
	v_lshl_add_u64 v[158:159], v[128:129], 0, v[156:157]
	v_mov_b32_e32 v128, v153
	s_lshl_b32 s55, s71, 8
	s_and_b32 s55, s55, 0x300
	v_ashrrev_i32_e32 v129, 1, v128
	v_and_b32_e32 v201, 0xffffffc0, v129
	v_and_b32_e32 v202, 48, v128
	v_lshrrev_b32_e32 v129, 2, v129
	v_bfe_u32 v204, v128, 2, 2
	v_mov_b32_e32 v205, v153
	v_and_b32_e32 v203, 8, v129
	v_or_b32_e32 v128, v202, v204
	v_add_u32_e32 v129, s55, v201
	v_or3_b32 v128, v129, v128, v203
	v_lshrrev_b32_e32 v130, 4, v205
	v_sub_u32_e32 v206, 0, v130
	v_ashrrev_i32_e32 v129, 31, v128
	v_xor_b32_e32 v130, v205, v206
	v_lshlrev_b64 v[128:129], 10, v[128:129]
	v_lshlrev_b32_e32 v130, 4, v130
	v_lshl_add_u64 v[128:129], s[24:25], 0, v[128:129]
	v_and_b32_e32 v156, 48, v130
	v_lshl_add_u64 v[160:161], v[128:129], 0, v[156:157]
	v_mov_b32_e32 v128, v153
	v_mov_b32_e32 v211, v153
	v_ashrrev_i32_e32 v129, 1, v128
	v_and_b32_e32 v208, 48, v128
	v_bfe_u32 v210, v128, 2, 2
	v_and_b32_e32 v207, 0xffffffc0, v129
	v_lshrrev_b32_e32 v129, 2, v129
	v_or3_b32 v128, v208, v210, s55
	v_and_b32_e32 v209, 8, v129
	v_add_u32_e32 v128, v207, v128
	v_or3_b32 v128, v128, v209, 4
	v_lshrrev_b32_e32 v130, 4, v211
	v_sub_u32_e32 v212, 0, v130
	v_ashrrev_i32_e32 v129, 31, v128
	v_xor_b32_e32 v130, v211, v212
	v_lshlrev_b64 v[128:129], 10, v[128:129]
	v_lshlrev_b32_e32 v130, 4, v130
	v_add_u32_e32 v166, s54, v149
	v_lshl_add_u64 v[128:129], s[24:25], 0, v[128:129]
	v_and_b32_e32 v156, 48, v130
	v_ashrrev_i32_e32 v167, 31, v166
	v_lshl_add_u64 v[164:165], v[128:129], 0, v[156:157]
	v_or_b32_e32 v168, s55, v151
	v_lshlrev_b64 v[128:129], 12, v[166:167]
	v_lshl_add_u64 v[128:129], s[12:13], 0, v[128:129]
	v_lshlrev_b32_e32 v156, 1, v168
	v_mov_b32_e32 v130, v153
	v_lshl_add_u64 v[170:171], v[128:129], 0, v[156:157]
	global_load_dwordx4 v[136:139], v[170:171], off offset:2048
	global_load_dwordx4 v[132:135], v[170:171], off offset:2064
	global_load_dwordx4 v[144:147], v[170:171], off
	global_load_dwordx4 v[140:143], v[170:171], off offset:16
	v_lshlrev_b32_e32 v128, 5, v130
	v_lshlrev_b32_e32 v129, 4, v130
	v_and_b32_e32 v128, 0xfffff800, v128
	v_and_b32_e32 v129, 0x3f0, v129
	v_add3_u32 v130, 0, v128, v129
	v_add_u32_e32 v129, 0x400, v130
	v_readfirstlane_b32 s54, v130
	v_add_u32_e32 v128, 0x4000, v130
	s_mov_b32 m0, s54
	v_readfirstlane_b32 s54, v129
	v_lshl_add_u64 v[162:163], v[158:159], 0, s[30:31]
	global_load_lds_dwordx4 v[158:159], off
	s_mov_b32 m0, s54
	v_readfirstlane_b32 s54, v128
	v_add_u32_e32 v128, 0x4400, v130
	global_load_lds_dwordx4 v[162:163], off
	s_mov_b32 m0, s54
	v_readfirstlane_b32 s54, v128
	v_add_u32_e32 v131, 0x8000, v130
	global_load_lds_dwordx4 v[160:161], off
	s_mov_b32 m0, s54
	v_readfirstlane_b32 s54, v131
	v_add_u32_e32 v131, 0x8400, v130
	global_load_lds_dwordx4 v[164:165], off
	v_add_u32_e32 v172, 0xc000, v130
	v_lshl_add_u64 v[128:129], v[158:159], 0, 64
	s_mov_b32 m0, s54
	v_readfirstlane_b32 s54, v131
	global_load_lds_dwordx4 v[128:129], off
	v_lshl_add_u64 v[128:129], v[158:159], 0, s[34:35]
	s_mov_b32 m0, s54
	v_readfirstlane_b32 s54, v172
	v_add_u32_e32 v131, 0xc400, v130
	global_load_lds_dwordx4 v[128:129], off
	v_lshl_add_u64 v[128:129], v[160:161], 0, 64
	s_mov_b32 m0, s54
	v_readfirstlane_b32 s54, v131
	v_add_u32_e32 v131, 0x10000, v130
	global_load_lds_dwordx4 v[128:129], off
	v_lshl_add_u64 v[128:129], v[164:165], 0, 64
	s_mov_b32 m0, s54
	v_readfirstlane_b32 s54, v131
	v_add_u32_e32 v131, 0x10400, v130
	global_load_lds_dwordx4 v[128:129], off
	v_add_u32_e32 v172, 0x14000, v130
	v_lshl_add_u64 v[128:129], v[158:159], 0, s[36:37]
	s_mov_b32 m0, s54
	v_readfirstlane_b32 s54, v131
	global_load_lds_dwordx4 v[128:129], off
	v_lshl_add_u64 v[128:129], v[158:159], 0, s[38:39]
	s_mov_b32 m0, s54
	v_readfirstlane_b32 s54, v172
	v_or_b32_e32 v172, 16, v166
	global_load_lds_dwordx4 v[128:129], off
	v_lshl_add_u64 v[128:129], v[160:161], 0, s[36:37]
	s_mov_b32 m0, s54
	v_ashrrev_i32_e32 v173, 31, v172
	global_load_lds_dwordx4 v[128:129], off
	v_lshlrev_b64 v[128:129], 12, v[172:173]
	v_lshl_add_u64 v[128:129], s[12:13], 0, v[128:129]
	v_lshl_add_u64 v[174:175], v[128:129], 0, v[156:157]
	global_load_dwordx4 v[180:183], v[174:175], off offset:2048
	global_load_dwordx4 v[184:187], v[174:175], off
	v_add_u32_e32 v130, 0x14400, v130
	v_lshl_add_u64 v[128:129], v[164:165], 0, s[36:37]
	v_readfirstlane_b32 s54, v130
	s_waitcnt vmcnt(0)
; __device__ __forceinline__ float frcp(float x) { return __builtin_amdgcn_rcpf(x); }
; __device__ __forceinline__ float bf2f(u16 h) { return __uint_as_float(((unsigned)h) << 16); }
; __device__ __forceinline__ void merge_phase(const Params& p, int first, int step, int n, char* lds) {
;     ...
;     cur = merge_ptrs(p, mt, nt, 1);
;     gemm_issue3(cur, lds);
; #pragma unroll
;     for (int i = 0; i < 8; ++i) {
;       const int m = mt * 256 + wm * 128 + i * 16 + lr;
;       const int n0 = nt * 256 + wn * 64 + lq * 16;
;       union { uint4 v[2]; u16 e[16]; } gh, gn;
;       gh.v[0] = *(const uint4*)(gates + (size_t)m * 2048 + n0); gh.v[1] = *(const uint4*)(gates + (size_t)m * 2048 + n0 + 8);
;       gn.v[0] = *(const uint4*)(gates + (size_t)m * 2048 + 1024 + n0); gn.v[1] = *(const uint4*)(gates + (size_t)m * 2048 + 1024 + n0 + 8);
; #pragma unroll
;       for (int j = 0; j < 4; ++j)
; #pragma unroll
;         for (int e = 0; e < 4; ++e) acc[i][j][e] *= bf2f(gh.e[j * 4 + e]) * frcp(bf2f(gn.e[j * 4 + e]));
;     }
	v_lshlrev_b32_e32 v130, 16, v136
	v_and_b32_e32 v131, 0xffff0000, v136
	v_rcp_f32_e32 v130, v130
	v_rcp_f32_e32 v131, v131
	s_mov_b32 m0, s54
	v_and_b32_e32 v136, 0xffff0000, v139
	global_load_lds_dwordx4 v[128:129], off
	v_and_b32_e32 v129, 0xffff0000, v144
	v_lshlrev_b32_e32 v128, 16, v144
	v_pk_mul_f32 v[128:129], v[130:131], v[128:129]
	v_lshlrev_b32_e32 v130, 16, v137
	v_and_b32_e32 v131, 0xffff0000, v137
	v_rcp_f32_e32 v130, v130
	v_rcp_f32_e32 v131, v131
	v_pk_mul_f32 v[0:1], v[0:1], v[128:129]
	v_and_b32_e32 v129, 0xffff0000, v145
	v_lshlrev_b32_e32 v128, 16, v145
	v_pk_mul_f32 v[128:129], v[130:131], v[128:129]
	v_lshlrev_b32_e32 v130, 16, v138
	v_and_b32_e32 v131, 0xffff0000, v138
	v_rcp_f32_e32 v130, v130
	v_rcp_f32_e32 v131, v131
	v_pk_mul_f32 v[2:3], v[2:3], v[128:129]
	v_and_b32_e32 v129, 0xffff0000, v146
	v_lshlrev_b32_e32 v128, 16, v146
	v_pk_mul_f32 v[128:129], v[130:131], v[128:129]
	v_rcp_f32_e32 v145, v136
	v_pk_mul_f32 v[4:5], v[4:5], v[128:129]
	v_lshlrev_b32_e32 v128, 16, v139
	v_rcp_f32_e32 v144, v128
	global_load_dwordx4 v[128:131], v[174:175], off offset:2064
	global_load_dwordx4 v[136:139], v[174:175], off offset:16
	v_lshlrev_b32_e32 v146, 16, v132
	v_and_b32_e32 v132, 0xffff0000, v132
	v_and_b32_e32 v177, 0xffff0000, v147
	v_lshlrev_b32_e32 v176, 16, v147
	v_rcp_f32_e32 v146, v146
	v_rcp_f32_e32 v147, v132
	v_pk_mul_f32 v[144:145], v[144:145], v[176:177]
	v_lshlrev_b32_e32 v132, 16, v133
	v_and_b32_e32 v133, 0xffff0000, v133
	v_pk_mul_f32 v[6:7], v[6:7], v[144:145]
	v_and_b32_e32 v145, 0xffff0000, v140
	v_lshlrev_b32_e32 v144, 16, v140
	v_rcp_f32_e32 v132, v132
	v_rcp_f32_e32 v133, v133
	v_pk_mul_f32 v[144:145], v[146:147], v[144:145]
	v_lshlrev_b32_e32 v140, 16, v134
	v_and_b32_e32 v134, 0xffff0000, v134
	v_pk_mul_f32 v[16:17], v[16:17], v[144:145]
	v_and_b32_e32 v145, 0xffff0000, v141
	v_lshlrev_b32_e32 v144, 16, v141
	v_rcp_f32_e32 v140, v140
	v_rcp_f32_e32 v141, v134
	v_pk_mul_f32 v[132:133], v[132:133], v[144:145]
	v_or_b32_e32 v176, 32, v166
	v_pk_mul_f32 v[18:19], v[18:19], v[132:133]
	v_and_b32_e32 v133, 0xffff0000, v142
	v_lshlrev_b32_e32 v132, 16, v142
	v_ashrrev_i32_e32 v177, 31, v176
	v_pk_mul_f32 v[132:133], v[140:141], v[132:133]
	v_lshlrev_b64 v[140:141], 12, v[176:177]
	v_lshl_add_u64 v[140:141], s[12:13], 0, v[140:141]
	v_lshl_add_u64 v[178:179], v[140:141], 0, v[156:157]
	global_load_dwordx4 v[144:147], v[178:179], off offset:2048
	v_pk_mul_f32 v[12:13], v[12:13], v[132:133]
	v_lshlrev_b32_e32 v132, 16, v135
	v_and_b32_e32 v133, 0xffff0000, v135
	v_rcp_f32_e32 v132, v132
	v_rcp_f32_e32 v133, v133
	global_load_dwordx4 v[188:191], v[178:179], off
	v_and_b32_e32 v135, 0xffff0000, v143
	v_lshlrev_b32_e32 v134, 16, v143
	v_pk_mul_f32 v[132:133], v[132:133], v[134:135]
	v_lshlrev_b32_e32 v134, 16, v180
	v_and_b32_e32 v135, 0xffff0000, v180
	v_rcp_f32_e32 v134, v134
	v_rcp_f32_e32 v135, v135
	v_pk_mul_f32 v[14:15], v[14:15], v[132:133]
	v_and_b32_e32 v133, 0xffff0000, v184
	v_lshlrev_b32_e32 v132, 16, v184
	v_pk_mul_f32 v[132:133], v[134:135], v[132:133]
	v_lshlrev_b32_e32 v134, 16, v181
	v_and_b32_e32 v135, 0xffff0000, v181
	v_rcp_f32_e32 v134, v134
	v_rcp_f32_e32 v135, v135
	v_pk_mul_f32 v[20:21], v[20:21], v[132:133]
	v_and_b32_e32 v133, 0xffff0000, v185
	v_lshlrev_b32_e32 v132, 16, v185
	v_pk_mul_f32 v[132:133], v[134:135], v[132:133]
	v_lshlrev_b32_e32 v134, 16, v182
	v_and_b32_e32 v135, 0xffff0000, v182
	v_rcp_f32_e32 v134, v134
	v_rcp_f32_e32 v135, v135
	v_pk_mul_f32 v[22:23], v[22:23], v[132:133]
	v_and_b32_e32 v133, 0xffff0000, v186
	v_lshlrev_b32_e32 v132, 16, v186
	v_pk_mul_f32 v[132:133], v[134:135], v[132:133]
	v_and_b32_e32 v140, 0xffff0000, v183
	v_pk_mul_f32 v[28:29], v[28:29], v[132:133]
	v_lshlrev_b32_e32 v132, 16, v183
	v_rcp_f32_e32 v180, v132
	global_load_dwordx4 v[132:135], v[178:179], off offset:2064
	v_rcp_f32_e32 v181, v140
	global_load_dwordx4 v[140:143], v[178:179], off offset:16
	v_and_b32_e32 v183, 0xffff0000, v187
	v_lshlrev_b32_e32 v182, 16, v187
	v_pk_mul_f32 v[180:181], v[180:181], v[182:183]
	v_or_b32_e32 v184, 64, v166
	v_pk_mul_f32 v[30:31], v[30:31], v[180:181]
	s_waitcnt vmcnt(0)
	v_lshlrev_b32_e32 v182, 16, v128
	v_and_b32_e32 v128, 0xffff0000, v128
	v_rcp_f32_e32 v182, v182
	v_rcp_f32_e32 v183, v128
	v_lshlrev_b32_e32 v128, 16, v129
	v_and_b32_e32 v129, 0xffff0000, v129
	v_and_b32_e32 v181, 0xffff0000, v136
	v_lshlrev_b32_e32 v180, 16, v136
	v_rcp_f32_e32 v128, v128
	v_rcp_f32_e32 v129, v129
	v_pk_mul_f32 v[180:181], v[182:183], v[180:181]
	v_lshlrev_b32_e32 v136, 16, v130
	v_and_b32_e32 v130, 0xffff0000, v130
	v_pk_mul_f32 v[48:49], v[48:49], v[180:181]
	v_and_b32_e32 v181, 0xffff0000, v137
	v_lshlrev_b32_e32 v180, 16, v137
	v_rcp_f32_e32 v136, v136
	v_rcp_f32_e32 v137, v130
	v_pk_mul_f32 v[128:129], v[128:129], v[180:181]
	v_or_b32_e32 v180, 48, v166
	v_pk_mul_f32 v[50:51], v[50:51], v[128:129]
	v_and_b32_e32 v129, 0xffff0000, v138
	v_lshlrev_b32_e32 v128, 16, v138
	v_ashrrev_i32_e32 v181, 31, v180
	v_pk_mul_f32 v[128:129], v[136:137], v[128:129]
	v_lshlrev_b64 v[136:137], 12, v[180:181]
	v_lshl_add_u64 v[136:137], s[12:13], 0, v[136:137]
	v_lshl_add_u64 v[182:183], v[136:137], 0, v[156:157]
	global_load_dwordx4 v[192:195], v[182:183], off offset:2048
	global_load_dwordx4 v[214:217], v[182:183], off
	v_pk_mul_f32 v[40:41], v[40:41], v[128:129]
	v_lshlrev_b32_e32 v128, 16, v131
	v_and_b32_e32 v129, 0xffff0000, v131
	v_rcp_f32_e32 v128, v128
	v_rcp_f32_e32 v129, v129
	v_and_b32_e32 v131, 0xffff0000, v139
	v_lshlrev_b32_e32 v130, 16, v139
	v_and_b32_e32 v136, 0xffff0000, v147
	v_pk_mul_f32 v[128:129], v[128:129], v[130:131]
	v_lshlrev_b32_e32 v130, 16, v144
; __device__ __forceinline__ float frcp(float x) { return __builtin_amdgcn_rcpf(x); }
; __device__ __forceinline__ float bf2f(u16 h) { return __uint_as_float(((unsigned)h) << 16); }
; __device__ __forceinline__ void merge_phase(const Params& p, int first, int step, int n, char* lds) {
;     ...
; #pragma unroll
;     for (int i = 0; i < 8; ++i) {
;       const int m = mt * 256 + wm * 128 + i * 16 + lr;
;       const int n0 = nt * 256 + wn * 64 + lq * 16;
;       union { uint4 v[2]; u16 e[16]; } gh, gn;
;       gh.v[0] = *(const uint4*)(gates + (size_t)m * 2048 + n0); gh.v[1] = *(const uint4*)(gates + (size_t)m * 2048 + n0 + 8);
;       gn.v[0] = *(const uint4*)(gates + (size_t)m * 2048 + 1024 + n0); gn.v[1] = *(const uint4*)(gates + (size_t)m * 2048 + 1024 + n0 + 8);
; #pragma unroll
;       for (int j = 0; j < 4; ++j)
; #pragma unroll
;         for (int e = 0; e < 4; ++e) acc[i][j][e] *= bf2f(gh.e[j * 4 + e]) * frcp(bf2f(gn.e[j * 4 + e]));
;     }
	v_and_b32_e32 v131, 0xffff0000, v144
	v_rcp_f32_e32 v130, v130
	v_rcp_f32_e32 v131, v131
	v_pk_mul_f32 v[42:43], v[42:43], v[128:129]
	v_and_b32_e32 v129, 0xffff0000, v188
	v_lshlrev_b32_e32 v128, 16, v188
	v_pk_mul_f32 v[128:129], v[130:131], v[128:129]
	v_lshlrev_b32_e32 v130, 16, v145
	v_and_b32_e32 v131, 0xffff0000, v145
	v_rcp_f32_e32 v130, v130
	v_rcp_f32_e32 v131, v131
	v_pk_mul_f32 v[52:53], v[52:53], v[128:129]
	v_and_b32_e32 v129, 0xffff0000, v189
	v_lshlrev_b32_e32 v128, 16, v189
	v_pk_mul_f32 v[128:129], v[130:131], v[128:129]
	v_lshlrev_b32_e32 v130, 16, v146
	v_and_b32_e32 v131, 0xffff0000, v146
	v_rcp_f32_e32 v130, v130
	v_rcp_f32_e32 v131, v131
	v_pk_mul_f32 v[54:55], v[54:55], v[128:129]
	v_and_b32_e32 v129, 0xffff0000, v190
	v_lshlrev_b32_e32 v128, 16, v190
	v_pk_mul_f32 v[128:129], v[130:131], v[128:129]
	v_rcp_f32_e32 v145, v136
	v_pk_mul_f32 v[56:57], v[56:57], v[128:129]
	v_lshlrev_b32_e32 v128, 16, v147
	v_rcp_f32_e32 v144, v128
	global_load_dwordx4 v[128:131], v[182:183], off offset:2064
	global_load_dwordx4 v[136:139], v[182:183], off offset:16
	v_and_b32_e32 v147, 0xffff0000, v191
	v_lshlrev_b32_e32 v146, 16, v191
	v_pk_mul_f32 v[144:145], v[144:145], v[146:147]
	v_lshlrev_b32_e32 v146, 16, v132
	v_and_b32_e32 v132, 0xffff0000, v132
	v_rcp_f32_e32 v146, v146
	v_rcp_f32_e32 v147, v132
	v_lshlrev_b32_e32 v132, 16, v133
	v_and_b32_e32 v133, 0xffff0000, v133
	v_pk_mul_f32 v[58:59], v[58:59], v[144:145]
	v_and_b32_e32 v145, 0xffff0000, v140
	v_lshlrev_b32_e32 v144, 16, v140
	v_rcp_f32_e32 v132, v132
	v_rcp_f32_e32 v133, v133
	v_pk_mul_f32 v[144:145], v[146:147], v[144:145]
	v_lshlrev_b32_e32 v140, 16, v134
	v_and_b32_e32 v134, 0xffff0000, v134
	v_pk_mul_f32 v[72:73], v[72:73], v[144:145]
	v_and_b32_e32 v145, 0xffff0000, v141
	v_lshlrev_b32_e32 v144, 16, v141
	v_rcp_f32_e32 v140, v140
	v_rcp_f32_e32 v141, v134
	v_pk_mul_f32 v[132:133], v[132:133], v[144:145]
	v_ashrrev_i32_e32 v185, 31, v184
	v_pk_mul_f32 v[74:75], v[74:75], v[132:133]
	v_and_b32_e32 v133, 0xffff0000, v142
	v_lshlrev_b32_e32 v132, 16, v142
	v_pk_mul_f32 v[132:133], v[140:141], v[132:133]
	v_lshlrev_b64 v[140:141], 12, v[184:185]
	v_lshl_add_u64 v[140:141], s[12:13], 0, v[140:141]
	v_lshl_add_u64 v[186:187], v[140:141], 0, v[156:157]
	global_load_dwordx4 v[218:221], v[186:187], off offset:2048
	v_pk_mul_f32 v[68:69], v[68:69], v[132:133]
	v_lshlrev_b32_e32 v132, 16, v135
	v_and_b32_e32 v133, 0xffff0000, v135
	v_rcp_f32_e32 v132, v132
	v_rcp_f32_e32 v133, v133
	global_load_dwordx4 v[222:225], v[186:187], off
	v_and_b32_e32 v135, 0xffff0000, v143
	v_lshlrev_b32_e32 v134, 16, v143
	v_pk_mul_f32 v[132:133], v[132:133], v[134:135]
	s_waitcnt vmcnt(0)
	v_lshlrev_b32_e32 v134, 16, v192
	v_and_b32_e32 v135, 0xffff0000, v192
	v_rcp_f32_e32 v134, v134
	v_rcp_f32_e32 v135, v135
	v_pk_mul_f32 v[70:71], v[70:71], v[132:133]
	v_and_b32_e32 v133, 0xffff0000, v214
	v_lshlrev_b32_e32 v132, 16, v214
	v_pk_mul_f32 v[132:133], v[134:135], v[132:133]
	v_lshlrev_b32_e32 v134, 16, v193
	v_and_b32_e32 v135, 0xffff0000, v193
	v_rcp_f32_e32 v134, v134
	v_rcp_f32_e32 v135, v135
	v_pk_mul_f32 v[76:77], v[76:77], v[132:133]
	v_and_b32_e32 v133, 0xffff0000, v215
	v_lshlrev_b32_e32 v132, 16, v215
	v_pk_mul_f32 v[132:133], v[134:135], v[132:133]
	v_lshlrev_b32_e32 v134, 16, v194
	v_and_b32_e32 v135, 0xffff0000, v194
	v_rcp_f32_e32 v134, v134
	v_rcp_f32_e32 v135, v135
	v_pk_mul_f32 v[78:79], v[78:79], v[132:133]
	v_and_b32_e32 v133, 0xffff0000, v216
	v_lshlrev_b32_e32 v132, 16, v216
	v_pk_mul_f32 v[132:133], v[134:135], v[132:133]
	global_load_dwordx4 v[142:145], v[186:187], off offset:16
	v_pk_mul_f32 v[80:81], v[80:81], v[132:133]
	v_lshlrev_b32_e32 v132, 16, v195
	v_rcp_f32_e32 v140, v132
	global_load_dwordx4 v[132:135], v[186:187], off offset:2064
	v_and_b32_e32 v141, 0xffff0000, v195
	v_rcp_f32_e32 v141, v141
	v_and_b32_e32 v147, 0xffff0000, v217
	v_lshlrev_b32_e32 v146, 16, v217
	v_or_b32_e32 v188, 0x50, v166
	v_pk_mul_f32 v[140:141], v[140:141], v[146:147]
	v_ashrrev_i32_e32 v189, 31, v188
	v_pk_mul_f32 v[82:83], v[82:83], v[140:141]
	v_lshlrev_b32_e32 v146, 16, v128
	v_and_b32_e32 v128, 0xffff0000, v128
	v_rcp_f32_e32 v146, v146
	v_rcp_f32_e32 v147, v128
	v_lshlrev_b32_e32 v128, 16, v129
	v_and_b32_e32 v129, 0xffff0000, v129
	v_and_b32_e32 v141, 0xffff0000, v136
	v_lshlrev_b32_e32 v140, 16, v136
	v_rcp_f32_e32 v128, v128
	v_rcp_f32_e32 v129, v129
	v_pk_mul_f32 v[140:141], v[146:147], v[140:141]
	v_lshlrev_b32_e32 v136, 16, v130
	v_and_b32_e32 v130, 0xffff0000, v130
	v_pk_mul_f32 v[100:101], v[100:101], v[140:141]
	v_and_b32_e32 v141, 0xffff0000, v137
	v_lshlrev_b32_e32 v140, 16, v137
	v_rcp_f32_e32 v136, v136
	v_rcp_f32_e32 v137, v130
	v_pk_mul_f32 v[128:129], v[128:129], v[140:141]
	v_lshlrev_b32_e32 v130, 16, v139
	v_pk_mul_f32 v[102:103], v[102:103], v[128:129]
	v_and_b32_e32 v129, 0xffff0000, v138
	v_lshlrev_b32_e32 v128, 16, v138
	v_pk_mul_f32 v[128:129], v[136:137], v[128:129]
	v_lshlrev_b64 v[136:137], 12, v[188:189]
	v_lshl_add_u64 v[136:137], s[12:13], 0, v[136:137]
	v_lshl_add_u64 v[190:191], v[136:137], 0, v[156:157]
	global_load_dwordx4 v[214:217], v[190:191], off offset:2048
	v_pk_mul_f32 v[96:97], v[96:97], v[128:129]
	v_lshlrev_b32_e32 v128, 16, v131
	v_and_b32_e32 v129, 0xffff0000, v131
	v_rcp_f32_e32 v128, v128
	v_rcp_f32_e32 v129, v129
	global_load_dwordx4 v[226:229], v[190:191], off
	v_and_b32_e32 v131, 0xffff0000, v139
	v_and_b32_e32 v136, 0xffff0000, v221
	v_pk_mul_f32 v[128:129], v[128:129], v[130:131]
	v_lshlrev_b32_e32 v130, 16, v218
	v_and_b32_e32 v131, 0xffff0000, v218
	v_rcp_f32_e32 v130, v130
	v_rcp_f32_e32 v131, v131
	v_pk_mul_f32 v[98:99], v[98:99], v[128:129]
	v_and_b32_e32 v129, 0xffff0000, v222
	v_lshlrev_b32_e32 v128, 16, v222
	v_pk_mul_f32 v[128:129], v[130:131], v[128:129]
	v_lshlrev_b32_e32 v130, 16, v219
	v_and_b32_e32 v131, 0xffff0000, v219
	v_rcp_f32_e32 v130, v130
	v_rcp_f32_e32 v131, v131
	v_pk_mul_f32 v[104:105], v[104:105], v[128:129]
	v_and_b32_e32 v129, 0xffff0000, v223
	v_lshlrev_b32_e32 v128, 16, v223
	v_pk_mul_f32 v[128:129], v[130:131], v[128:129]
	v_lshlrev_b32_e32 v130, 16, v220
	v_and_b32_e32 v131, 0xffff0000, v220
	v_rcp_f32_e32 v130, v130
	v_rcp_f32_e32 v131, v131
	v_pk_mul_f32 v[106:107], v[106:107], v[128:129]
	v_and_b32_e32 v129, 0xffff0000, v224
	v_lshlrev_b32_e32 v128, 16, v224
	v_pk_mul_f32 v[128:129], v[130:131], v[128:129]
	v_rcp_f32_e32 v141, v136
	v_pk_mul_f32 v[108:109], v[108:109], v[128:129]
	v_lshlrev_b32_e32 v128, 16, v221
	v_rcp_f32_e32 v140, v128
	global_load_dwordx4 v[128:131], v[190:191], off offset:2064
	global_load_dwordx4 v[136:139], v[190:191], off offset:16
	v_and_b32_e32 v147, 0xffff0000, v225
	v_lshlrev_b32_e32 v146, 16, v225
	v_pk_mul_f32 v[140:141], v[140:141], v[146:147]
	v_or_b32_e32 v192, 0x60, v166
	s_waitcnt vmcnt(0)
; __device__ __forceinline__ float frcp(float x) { return __builtin_amdgcn_rcpf(x); }
; __device__ __forceinline__ float bf2f(u16 h) { return __uint_as_float(((unsigned)h) << 16); }
; __device__ __forceinline__ void merge_phase(const Params& p, int first, int step, int n, char* lds) {
;     ...
; #pragma unroll
;     for (int i = 0; i < 8; ++i) {
;       const int m = mt * 256 + wm * 128 + i * 16 + lr;
;       const int n0 = nt * 256 + wn * 64 + lq * 16;
;       union { uint4 v[2]; u16 e[16]; } gh, gn;
;       gh.v[0] = *(const uint4*)(gates + (size_t)m * 2048 + n0); gh.v[1] = *(const uint4*)(gates + (size_t)m * 2048 + n0 + 8);
;       gn.v[0] = *(const uint4*)(gates + (size_t)m * 2048 + 1024 + n0); gn.v[1] = *(const uint4*)(gates + (size_t)m * 2048 + 1024 + n0 + 8);
; #pragma unroll
;       for (int j = 0; j < 4; ++j)
; #pragma unroll
;         for (int e = 0; e < 4; ++e) acc[i][j][e] *= bf2f(gh.e[j * 4 + e]) * frcp(bf2f(gn.e[j * 4 + e]));
;     }
	v_lshlrev_b32_e32 v146, 16, v132
	v_and_b32_e32 v132, 0xffff0000, v132
	v_rcp_f32_e32 v146, v146
	v_rcp_f32_e32 v147, v132
	v_lshlrev_b32_e32 v132, 16, v133
	v_and_b32_e32 v133, 0xffff0000, v133
	v_rcp_f32_e32 v132, v132
	v_rcp_f32_e32 v133, v133
	v_pk_mul_f32 v[110:111], v[110:111], v[140:141]
	v_and_b32_e32 v141, 0xffff0000, v142
	v_lshlrev_b32_e32 v140, 16, v142
	v_pk_mul_f32 v[140:141], v[146:147], v[140:141]
	v_ashrrev_i32_e32 v193, 31, v192
	v_pk_mul_f32 v[120:121], v[120:121], v[140:141]
	v_and_b32_e32 v141, 0xffff0000, v143
	v_lshlrev_b32_e32 v140, 16, v143
	v_pk_mul_f32 v[132:133], v[132:133], v[140:141]
	v_lshlrev_b32_e32 v140, 16, v134
	v_and_b32_e32 v134, 0xffff0000, v134
	v_rcp_f32_e32 v140, v140
	v_rcp_f32_e32 v141, v134
	v_pk_mul_f32 v[122:123], v[122:123], v[132:133]
	v_and_b32_e32 v133, 0xffff0000, v144
	v_lshlrev_b32_e32 v132, 16, v144
	v_pk_mul_f32 v[132:133], v[140:141], v[132:133]
	v_and_b32_e32 v219, 0xffff0000, v145
	v_pk_mul_f32 v[116:117], v[116:117], v[132:133]
	v_lshlrev_b32_e32 v132, 16, v135
	v_rcp_f32_e32 v146, v132
	v_lshlrev_b64 v[132:133], 12, v[192:193]
	v_lshl_add_u64 v[132:133], s[12:13], 0, v[132:133]
	v_lshl_add_u64 v[194:195], v[132:133], 0, v[156:157]
	global_load_dwordx4 v[140:143], v[194:195], off offset:2048
	v_and_b32_e32 v132, 0xffff0000, v135
	v_rcp_f32_e32 v147, v132
	global_load_dwordx4 v[132:135], v[194:195], off
	v_lshlrev_b32_e32 v218, 16, v145
	v_and_b32_e32 v213, 0xffff0000, v217
	v_pk_mul_f32 v[144:145], v[146:147], v[218:219]
	v_lshlrev_b32_e32 v146, 16, v214
	v_and_b32_e32 v147, 0xffff0000, v214
	v_rcp_f32_e32 v146, v146
	v_rcp_f32_e32 v147, v147
	v_pk_mul_f32 v[118:119], v[118:119], v[144:145]
	v_and_b32_e32 v145, 0xffff0000, v226
	v_lshlrev_b32_e32 v144, 16, v226
	v_pk_mul_f32 v[144:145], v[146:147], v[144:145]
	v_lshlrev_b32_e32 v146, 16, v215
	v_and_b32_e32 v147, 0xffff0000, v215
	v_rcp_f32_e32 v146, v146
	v_rcp_f32_e32 v147, v147
	v_pk_mul_f32 v[124:125], v[124:125], v[144:145]
	v_and_b32_e32 v145, 0xffff0000, v227
	v_lshlrev_b32_e32 v144, 16, v227
	v_pk_mul_f32 v[144:145], v[146:147], v[144:145]
	v_lshlrev_b32_e32 v146, 16, v216
	v_and_b32_e32 v147, 0xffff0000, v216
	v_rcp_f32_e32 v146, v146
	v_rcp_f32_e32 v147, v147
	v_pk_mul_f32 v[126:127], v[126:127], v[144:145]
	v_and_b32_e32 v145, 0xffff0000, v228
	v_lshlrev_b32_e32 v144, 16, v228
	v_pk_mul_f32 v[144:145], v[146:147], v[144:145]
	v_rcp_f32_e32 v219, v213
	v_pk_mul_f32 v[112:113], v[112:113], v[144:145]
	v_lshlrev_b32_e32 v144, 16, v217
	v_rcp_f32_e32 v218, v144
	global_load_dwordx4 v[144:147], v[194:195], off offset:2064
	global_load_dwordx4 v[214:217], v[194:195], off offset:16
	v_and_b32_e32 v221, 0xffff0000, v229
	v_lshlrev_b32_e32 v220, 16, v229
	v_pk_mul_f32 v[218:219], v[218:219], v[220:221]
	s_and_b32 s47, s70, 0xffffff00
	v_pk_mul_f32 v[114:115], v[114:115], v[218:219]
	v_lshlrev_b32_e32 v213, 16, v128
	v_and_b32_e32 v128, 0xffff0000, v128
	v_rcp_f32_e32 v220, v213
	v_rcp_f32_e32 v221, v128
	v_lshlrev_b32_e32 v128, 16, v129
	v_and_b32_e32 v129, 0xffff0000, v129
	v_rcp_f32_e32 v128, v128
	v_rcp_f32_e32 v129, v129
	v_and_b32_e32 v219, 0xffff0000, v136
	v_lshlrev_b32_e32 v218, 16, v136
	v_pk_mul_f32 v[218:219], v[220:221], v[218:219]
	s_and_b32 s46, s69, 0x300
	v_pk_mul_f32 v[92:93], v[92:93], v[218:219]
	v_and_b32_e32 v219, 0xffff0000, v137
	v_lshlrev_b32_e32 v218, 16, v137
	v_pk_mul_f32 v[222:223], v[128:129], v[218:219]
	v_lshlrev_b32_e32 v128, 16, v130
	v_rcp_f32_e32 v224, v128
	v_and_b32_e32 v128, 0xffff0000, v130
	v_rcp_f32_e32 v225, v128
	v_or_b32_e32 v128, 0x70, v166
	v_ashrrev_i32_e32 v129, 31, v128
	v_lshlrev_b64 v[136:137], 12, v[128:129]
	v_lshl_add_u64 v[136:137], s[12:13], 0, v[136:137]
	v_lshl_add_u64 v[136:137], v[136:137], 0, v[156:157]
	global_load_dwordx4 v[218:221], v[136:137], off offset:2048
	v_pk_mul_f32 v[94:95], v[94:95], v[222:223]
	v_and_b32_e32 v223, 0xffff0000, v138
	v_lshlrev_b32_e32 v222, 16, v138
	v_pk_mul_f32 v[226:227], v[224:225], v[222:223]
	global_load_dwordx4 v[222:225], v[136:137], off
	v_lshlrev_b32_e32 v130, 16, v131
	v_and_b32_e32 v131, 0xffff0000, v131
	v_rcp_f32_e32 v130, v130
	v_rcp_f32_e32 v131, v131
	v_pk_mul_f32 v[88:89], v[88:89], v[226:227]
	v_and_b32_e32 v227, 0xffff0000, v139
	v_lshlrev_b32_e32 v226, 16, v139
	s_waitcnt vmcnt(0)
; __device__ __forceinline__ int otid() { int t = threadIdx.x; asm volatile("" : "+v"(t)); return t; }
; __device__ __forceinline__ float frcp(float x) { return __builtin_amdgcn_rcpf(x); }
; __device__ __forceinline__ float bf2f(u16 h) { return __uint_as_float(((unsigned)h) << 16); }
; #define GEMM_WAITV(n) asm volatile("s_waitcnt vmcnt(" #n ")" ::: "memory")
; template <bool SWAP>
; __device__ __forceinline__ void gemm_main(f32x4 (&acc)[8][4], const TP& t, int nk, char* lds) {
;   const u16* a0 = t.a0; const u16* a1 = t.a1; const u16* b0 = t.b0; const u16* b1 = t.b1;
;   const int tid = otid(), lane = tid & 63, wave = tid >> 6;
;   const int wm = wave >> 2, wn = wave & 3, lr = lane & 15, lq = lane >> 4;
;   const int ldoff = wave * 2048 + lane * 16;
;   const int sw = (lq ^ ((0 - (lr >> 2)) & 3)) << 4;
;   const int aoff = (wm * 128 + lr) * 64 + sw, boff = T_ASTAGE + (wn * 64 + lr) * 64 + sw;
;     ...
; #pragma unroll 1
;   for (int kt = 0; kt < nk - 3; ++kt) {
;     GEMM_WAITV(8);
;     GEMM_STEP(kt, true)
; __device__ __forceinline__ void merge_phase(const Params& p, int first, int step, int n, char* lds) {
;     ...
; #pragma unroll
;     for (int i = 0; i < 8; ++i) {
;       const int m = mt * 256 + wm * 128 + i * 16 + lr;
;       const int n0 = nt * 256 + wn * 64 + lq * 16;
;       union { uint4 v[2]; u16 e[16]; } gh, gn;
;       gh.v[0] = *(const uint4*)(gates + (size_t)m * 2048 + n0); gh.v[1] = *(const uint4*)(gates + (size_t)m * 2048 + n0 + 8);
;       gn.v[0] = *(const uint4*)(gates + (size_t)m * 2048 + 1024 + n0); gn.v[1] = *(const uint4*)(gates + (size_t)m * 2048 + 1024 + n0 + 8);
; #pragma unroll
;       for (int j = 0; j < 4; ++j)
; #pragma unroll
;         for (int e = 0; e < 4; ++e) acc[i][j][e] *= bf2f(gh.e[j * 4 + e]) * frcp(bf2f(gn.e[j * 4 + e]));
;     }
	v_lshlrev_b32_e32 v138, 16, v140
	v_and_b32_e32 v139, 0xffff0000, v140
	v_rcp_f32_e32 v138, v138
	v_rcp_f32_e32 v139, v139
	v_pk_mul_f32 v[130:131], v[130:131], v[226:227]
	v_and_b32_e32 v229, 0xffff0000, v134
	v_pk_mul_f32 v[90:91], v[90:91], v[130:131]
	v_and_b32_e32 v131, 0xffff0000, v132
	v_lshlrev_b32_e32 v130, 16, v132
	v_lshlrev_b32_e32 v132, 16, v141
	v_pk_mul_f32 v[130:131], v[138:139], v[130:131]
	v_rcp_f32_e32 v138, v132
	v_and_b32_e32 v132, 0xffff0000, v141
	v_rcp_f32_e32 v139, v132
	v_pk_mul_f32 v[84:85], v[84:85], v[130:131]
	v_and_b32_e32 v131, 0xffff0000, v133
	v_lshlrev_b32_e32 v130, 16, v133
	v_pk_mul_f32 v[130:131], v[138:139], v[130:131]
	v_lshlrev_b32_e32 v138, 16, v142
	v_pk_mul_f32 v[86:87], v[86:87], v[130:131]
	global_load_dwordx4 v[130:133], v[136:137], off offset:2064
	v_rcp_f32_e32 v226, v138
	v_and_b32_e32 v138, 0xffff0000, v142
	v_rcp_f32_e32 v227, v138
	global_load_dwordx4 v[138:141], v[136:137], off offset:16
	v_lshlrev_b32_e32 v228, 16, v134
	v_lshlrev_b32_e32 v134, 16, v143
	v_rcp_f32_e32 v142, v134
	v_and_b32_e32 v134, 0xffff0000, v143
	v_rcp_f32_e32 v143, v134
	v_pk_mul_f32 v[226:227], v[226:227], v[228:229]
	s_mov_b32 s54, 0x18000
	v_pk_mul_f32 v[64:65], v[64:65], v[226:227]
	v_and_b32_e32 v227, 0xffff0000, v135
	v_lshlrev_b32_e32 v226, 16, v135
	v_pk_mul_f32 v[134:135], v[142:143], v[226:227]
	v_lshlrev_b32_e32 v142, 16, v144
	v_and_b32_e32 v143, 0xffff0000, v144
	v_rcp_f32_e32 v142, v142
	v_rcp_f32_e32 v143, v143
	v_pk_mul_f32 v[66:67], v[66:67], v[134:135]
	v_and_b32_e32 v135, 0xffff0000, v214
	v_lshlrev_b32_e32 v134, 16, v214
	v_pk_mul_f32 v[134:135], v[142:143], v[134:135]
	v_lshlrev_b32_e32 v142, 16, v145
	v_and_b32_e32 v143, 0xffff0000, v145
	v_rcp_f32_e32 v142, v142
	v_rcp_f32_e32 v143, v143
	v_pk_mul_f32 v[60:61], v[60:61], v[134:135]
	v_and_b32_e32 v135, 0xffff0000, v215
	v_lshlrev_b32_e32 v134, 16, v215
	v_pk_mul_f32 v[134:135], v[142:143], v[134:135]
	v_lshlrev_b32_e32 v142, 16, v146
	v_and_b32_e32 v143, 0xffff0000, v146
	v_rcp_f32_e32 v142, v142
	v_rcp_f32_e32 v143, v143
	v_pk_mul_f32 v[62:63], v[62:63], v[134:135]
	v_and_b32_e32 v135, 0xffff0000, v216
	v_lshlrev_b32_e32 v134, 16, v216
	v_pk_mul_f32 v[134:135], v[142:143], v[134:135]
	v_lshlrev_b32_e32 v142, 16, v147
	v_and_b32_e32 v143, 0xffff0000, v147
	v_rcp_f32_e32 v142, v142
	v_rcp_f32_e32 v143, v143
	v_pk_mul_f32 v[44:45], v[44:45], v[134:135]
	v_and_b32_e32 v135, 0xffff0000, v217
	v_lshlrev_b32_e32 v134, 16, v217
	v_pk_mul_f32 v[134:135], v[142:143], v[134:135]
	v_lshlrev_b32_e32 v142, 16, v218
	v_and_b32_e32 v143, 0xffff0000, v218
	v_rcp_f32_e32 v142, v142
	v_rcp_f32_e32 v143, v143
	v_pk_mul_f32 v[46:47], v[46:47], v[134:135]
	v_and_b32_e32 v135, 0xffff0000, v222
	v_lshlrev_b32_e32 v134, 16, v222
	v_pk_mul_f32 v[134:135], v[142:143], v[134:135]
	v_lshlrev_b32_e32 v142, 16, v219
	v_and_b32_e32 v143, 0xffff0000, v219
	v_rcp_f32_e32 v142, v142
	v_rcp_f32_e32 v143, v143
	v_pk_mul_f32 v[36:37], v[36:37], v[134:135]
	v_and_b32_e32 v135, 0xffff0000, v223
	v_lshlrev_b32_e32 v134, 16, v223
	v_pk_mul_f32 v[134:135], v[142:143], v[134:135]
	v_lshlrev_b32_e32 v142, 16, v220
	v_and_b32_e32 v143, 0xffff0000, v220
	v_rcp_f32_e32 v142, v142
	v_rcp_f32_e32 v143, v143
	v_pk_mul_f32 v[38:39], v[38:39], v[134:135]
	v_and_b32_e32 v135, 0xffff0000, v224
	v_lshlrev_b32_e32 v134, 16, v224
	v_pk_mul_f32 v[134:135], v[142:143], v[134:135]
	v_lshlrev_b32_e32 v142, 16, v221
	v_and_b32_e32 v143, 0xffff0000, v221
	v_rcp_f32_e32 v142, v142
	v_rcp_f32_e32 v143, v143
	v_pk_mul_f32 v[32:33], v[32:33], v[134:135]
	v_and_b32_e32 v135, 0xffff0000, v225
	v_lshlrev_b32_e32 v134, 16, v225
	v_pk_mul_f32 v[134:135], v[142:143], v[134:135]
	s_waitcnt vmcnt(0)
	v_lshlrev_b32_e32 v142, 16, v130
	v_and_b32_e32 v130, 0xffff0000, v130
	v_rcp_f32_e32 v142, v142
	v_rcp_f32_e32 v143, v130
	v_lshlrev_b32_e32 v130, 16, v131
	v_and_b32_e32 v131, 0xffff0000, v131
	v_rcp_f32_e32 v130, v130
	v_rcp_f32_e32 v131, v131
	v_pk_mul_f32 v[34:35], v[34:35], v[134:135]
	v_and_b32_e32 v135, 0xffff0000, v138
	v_lshlrev_b32_e32 v134, 16, v138
	v_pk_mul_f32 v[134:135], v[142:143], v[134:135]
	v_bitop3_b32 v145, v211, 3, v212 bitop3:0x48
	v_pk_mul_f32 v[24:25], v[24:25], v[134:135]
	v_and_b32_e32 v135, 0xffff0000, v139
	v_lshlrev_b32_e32 v134, 16, v139
	v_pk_mul_f32 v[130:131], v[130:131], v[134:135]
	v_lshlrev_b32_e32 v134, 16, v132
	v_and_b32_e32 v132, 0xffff0000, v132
	v_rcp_f32_e32 v134, v134
	v_rcp_f32_e32 v135, v132
	v_lshlrev_b32_e32 v132, 16, v133
	v_and_b32_e32 v133, 0xffff0000, v133
	v_rcp_f32_e32 v132, v132
	v_rcp_f32_e32 v133, v133
	v_pk_mul_f32 v[26:27], v[26:27], v[130:131]
	v_and_b32_e32 v131, 0xffff0000, v140
	v_lshlrev_b32_e32 v130, 16, v140
	v_pk_mul_f32 v[130:131], v[134:135], v[130:131]
	v_bitop3_b32 v134, v205, 3, v206 bitop3:0x48
	v_pk_mul_f32 v[8:9], v[8:9], v[130:131]
	v_and_b32_e32 v131, 0xffff0000, v141
	v_lshlrev_b32_e32 v130, 16, v141
	v_pk_mul_f32 v[130:131], v[132:133], v[130:131]
	s_nop 0
	v_pk_mul_f32 v[10:11], v[10:11], v[130:131]
	v_mov_b32_e32 v130, v153
	s_nop 0
	v_lshlrev_b32_e32 v133, 2, v130
	v_and_b32_e32 v133, 48, v133
	v_sub_u32_e32 v133, 0, v133
	v_and_b32_e32 v138, 15, v130
	v_lshlrev_b32_e32 v131, 5, v130
	v_lshlrev_b32_e32 v132, 4, v130
	v_bitop3_b32 v139, v130, 48, v133 bitop3:0x48
	v_ashrrev_i32_e32 v140, 1, v130
	v_lshlrev_b32_e32 v130, 6, v130
	v_and_b32_e32 v142, 0x33c0, v130
	v_add_u32_e32 v130, s47, v155
	v_and_b32_e32 v131, 0xfffff800, v131
	v_and_b32_e32 v132, 0x3f0, v132
	v_or_b32_e32 v130, v130, v198
	v_add3_u32 v144, 0, v131, v132
	v_ashrrev_i32_e32 v131, 31, v130
	v_lshlrev_b64 v[130:131], 10, v[130:131]
	v_bitop3_b32 v132, v199, 3, v200 bitop3:0x48
	v_lshl_or_b32 v130, v132, 4, v130
	v_add_u32_e32 v132, s46, v201
	v_or_b32_e32 v132, v132, v202
	v_and_or_b32 v133, v140, s68, v138
	v_or3_b32 v132, v132, v203, v204
	v_lshl_or_b32 v141, v133, 6, v139
	v_ashrrev_i32_e32 v133, 31, v132
	v_lshlrev_b64 v[132:133], 10, v[132:133]
	v_lshl_or_b32 v132, v134, 4, v132
	v_add_u32_e32 v134, s46, v207
	v_or3_b32 v134, v134, v208, v209
	v_or3_b32 v134, v134, v210, 4
	v_ashrrev_i32_e32 v135, 31, v134
	v_lshlrev_b64 v[134:135], 10, v[134:135]
	v_lshl_or_b32 v134, v145, 4, v134
	v_or_b32_e32 v143, v142, v139
	v_lshl_add_u64 v[130:131], s[48:49], 0, v[130:131]
	v_lshl_add_u64 v[132:133], s[26:27], 0, v[132:133]
	v_lshl_add_u64 v[134:135], s[26:27], 0, v[134:135]
	s_mov_b64 s[46:47], 0
	v_readfirstlane_b32 s98, v144
	s_add_i32 s55, s54, 0xfffe8000
	s_and_b32 s55, s55, 0x18000
	v_add_u32_e32 v235, s55, v141
	v_add_u32_e32 v236, s55, v143
	s_waitcnt vmcnt(8)
	s_barrier
	ds_read_b128 v[214:217], v235
	ds_read_b128 v[218:221], v235 offset:1024
	ds_read_b128 v[198:201], v236 offset:16384
	ds_read_b128 v[202:205], v236 offset:17408
	ds_read_b128 v[206:209], v236 offset:18432
	ds_read_b128 v[210:213], v236 offset:19456
	ds_read_b128 v[222:225], v235 offset:2048
	ds_read_b128 v[226:229], v235 offset:3072
	s_branch .Lmg2_mid
; __device__ __forceinline__ int otid() { int t = threadIdx.x; asm volatile("" : "+v"(t)); return t; }
; #define GEMM_WAITV(n) asm volatile("s_waitcnt vmcnt(" #n ")" ::: "memory")
; template <bool SWAP>
; __device__ __forceinline__ void gemm_main(f32x4 (&acc)[8][4], const TP& t, int nk, char* lds) {
;   const u16* a0 = t.a0; const u16* a1 = t.a1; const u16* b0 = t.b0; const u16* b1 = t.b1;
;   const int tid = otid(), lane = tid & 63, wave = tid >> 6;
;   const int wm = wave >> 2, wn = wave & 3, lr = lane & 15, lq = lane >> 4;
;   const int ldoff = wave * 2048 + lane * 16;
;   const int sw = (lq ^ ((0 - (lr >> 2)) & 3)) << 4;
;   const int aoff = (wm * 128 + lr) * 64 + sw, boff = T_ASTAGE + (wn * 64 + lr) * 64 + sw;
;     ...
; #pragma unroll 1
;   for (int kt = 0; kt < nk - 3; ++kt) {
;     GEMM_WAITV(8);
;     GEMM_STEP(kt, true)
;   }
; #pragma unroll 1
;   for (int kt = nk - 3; kt < nk; ++kt) {
;     const int rem = nk - kt;
;     if (rem == 3) GEMM_WAITV(8); else if (rem == 2) GEMM_WAITV(4); else GEMM_WAITV(0);
;     GEMM_STEP(kt, false)
;   }
.Lmg2_top:
	s_add_i32 s55, s54, 0xfffe8000
	s_and_b32 s55, s55, 0x18000
	v_add_u32_e32 v235, s55, v141
	v_add_u32_e32 v236, s55, v143
	s_waitcnt vmcnt(8)
	s_barrier
	ds_read_b128 v[214:217], v235
	ds_read_b128 v[218:221], v235 offset:1024
	v_mfma_f32_16x16x32_bf16 v[84:87], v[198:201], v[222:225], v[84:87]
	v_mfma_f32_16x16x32_bf16 v[36:39], v[198:201], v[226:229], v[36:39]
	ds_read_b128 v[198:201], v236 offset:16384
	v_mfma_f32_16x16x32_bf16 v[64:67], v[202:205], v[222:225], v[64:67]
	v_mfma_f32_16x16x32_bf16 v[32:35], v[202:205], v[226:229], v[32:35]
	ds_read_b128 v[202:205], v236 offset:17408
	v_mfma_f32_16x16x32_bf16 v[60:63], v[206:209], v[222:225], v[60:63]
	v_mfma_f32_16x16x32_bf16 v[24:27], v[206:209], v[226:229], v[24:27]
	ds_read_b128 v[206:209], v236 offset:18432
	v_mfma_f32_16x16x32_bf16 v[44:47], v[210:213], v[222:225], v[44:47]
	v_mfma_f32_16x16x32_bf16 v[8:11], v[210:213], v[226:229], v[8:11]
	ds_read_b128 v[210:213], v236 offset:19456
	ds_read_b128 v[222:225], v235 offset:2048
	ds_read_b128 v[226:229], v235 offset:3072
.Lmg2_mid:
	s_and_b32 s55, s54, 0x18000
	s_add_i32 s55, s55, s98
	s_mov_b32 m0, s55
	v_lshl_add_u64 v[146:147], v[130:131], 0, s[46:47]
	v_lshl_add_u64 v[238:239], v[146:147], 0, s[42:43]
	s_waitcnt lgkmcnt(5)
	v_mfma_f32_16x16x32_bf16 v[0:3], v[198:201], v[214:217], v[0:3]
	global_load_lds_dwordx4 v[238:239], off
	s_waitcnt lgkmcnt(4)
	v_mfma_f32_16x16x32_bf16 v[4:7], v[202:205], v[214:217], v[4:7]
	s_waitcnt lgkmcnt(3)
	v_mfma_f32_16x16x32_bf16 v[16:19], v[206:209], v[214:217], v[16:19]
	s_waitcnt lgkmcnt(2)
	v_mfma_f32_16x16x32_bf16 v[12:15], v[210:213], v[214:217], v[12:15]
	v_mfma_f32_16x16x32_bf16 v[20:23], v[198:201], v[218:221], v[20:23]
	v_mfma_f32_16x16x32_bf16 v[28:31], v[202:205], v[218:221], v[28:31]
	v_mfma_f32_16x16x32_bf16 v[48:51], v[206:209], v[218:221], v[48:51]
	v_mfma_f32_16x16x32_bf16 v[40:43], v[210:213], v[218:221], v[40:43]
	ds_read_b128 v[214:217], v235 offset:4096
	ds_read_b128 v[218:221], v235 offset:5120
	s_add_i32 m0, s55, 0x400
	v_lshl_add_u64 v[238:239], v[146:147], 0, s[44:45]
	s_waitcnt lgkmcnt(3)
	v_mfma_f32_16x16x32_bf16 v[52:55], v[198:201], v[222:225], v[52:55]
	global_load_lds_dwordx4 v[238:239], off
	v_mfma_f32_16x16x32_bf16 v[56:59], v[202:205], v[222:225], v[56:59]
	v_mfma_f32_16x16x32_bf16 v[72:75], v[206:209], v[222:225], v[72:75]
	v_mfma_f32_16x16x32_bf16 v[68:71], v[210:213], v[222:225], v[68:71]
	s_waitcnt lgkmcnt(2)
	v_mfma_f32_16x16x32_bf16 v[76:79], v[198:201], v[226:229], v[76:79]
	v_mfma_f32_16x16x32_bf16 v[80:83], v[202:205], v[226:229], v[80:83]
	v_mfma_f32_16x16x32_bf16 v[100:103], v[206:209], v[226:229], v[100:103]
	v_mfma_f32_16x16x32_bf16 v[96:99], v[210:213], v[226:229], v[96:99]
	ds_read_b128 v[222:225], v235 offset:6144
	ds_read_b128 v[226:229], v235 offset:7168
	s_add_i32 m0, s55, 0x4000
	v_lshl_add_u64 v[238:239], v[132:133], 0, s[46:47]
	s_waitcnt lgkmcnt(3)
	v_mfma_f32_16x16x32_bf16 v[104:107], v[198:201], v[214:217], v[104:107]
	global_load_lds_dwordx4 v[238:239], off
	v_mfma_f32_16x16x32_bf16 v[108:111], v[202:205], v[214:217], v[108:111]
	v_mfma_f32_16x16x32_bf16 v[120:123], v[206:209], v[214:217], v[120:123]
	v_mfma_f32_16x16x32_bf16 v[116:119], v[210:213], v[214:217], v[116:119]
	s_add_i32 m0, s55, 0x4400
	v_lshl_add_u64 v[238:239], v[134:135], 0, s[46:47]
	s_waitcnt lgkmcnt(2)
	v_mfma_f32_16x16x32_bf16 v[124:127], v[198:201], v[218:221], v[124:127]
	global_load_lds_dwordx4 v[238:239], off
	v_mfma_f32_16x16x32_bf16 v[112:115], v[202:205], v[218:221], v[112:115]
	s_add_u32 s46, s46, 64
	s_addc_u32 s47, s47, 0
	s_add_i32 s54, s54, 0x8000
	v_mfma_f32_16x16x32_bf16 v[92:95], v[206:209], v[218:221], v[92:95]
	v_mfma_f32_16x16x32_bf16 v[88:91], v[210:213], v[218:221], v[88:91]
	s_waitcnt lgkmcnt(0)
	s_cmpk_lg_i32 s46, 0x340
	s_cbranch_scc1 .Lmg2_top
	v_add_u32_e32 v235, 0x8000, v141
	v_add_u32_e32 v236, 0x8000, v143
	s_waitcnt vmcnt(8)
	s_barrier
	ds_read_b128 v[214:217], v235
	ds_read_b128 v[218:221], v235 offset:1024
	v_mfma_f32_16x16x32_bf16 v[84:87], v[198:201], v[222:225], v[84:87]
	v_mfma_f32_16x16x32_bf16 v[36:39], v[198:201], v[226:229], v[36:39]
	ds_read_b128 v[198:201], v236 offset:16384
	v_mfma_f32_16x16x32_bf16 v[64:67], v[202:205], v[222:225], v[64:67]
	v_mfma_f32_16x16x32_bf16 v[32:35], v[202:205], v[226:229], v[32:35]
	ds_read_b128 v[202:205], v236 offset:17408
	v_mfma_f32_16x16x32_bf16 v[60:63], v[206:209], v[222:225], v[60:63]
	v_mfma_f32_16x16x32_bf16 v[24:27], v[206:209], v[226:229], v[24:27]
	ds_read_b128 v[206:209], v236 offset:18432
	v_mfma_f32_16x16x32_bf16 v[44:47], v[210:213], v[222:225], v[44:47]
	v_mfma_f32_16x16x32_bf16 v[8:11], v[210:213], v[226:229], v[8:11]
	ds_read_b128 v[210:213], v236 offset:19456
	ds_read_b128 v[222:225], v235 offset:2048
	ds_read_b128 v[226:229], v235 offset:3072
	s_waitcnt lgkmcnt(5)
	v_mfma_f32_16x16x32_bf16 v[0:3], v[198:201], v[214:217], v[0:3]
	s_waitcnt lgkmcnt(4)
	v_mfma_f32_16x16x32_bf16 v[4:7], v[202:205], v[214:217], v[4:7]
	s_waitcnt lgkmcnt(3)
	v_mfma_f32_16x16x32_bf16 v[16:19], v[206:209], v[214:217], v[16:19]
	s_waitcnt lgkmcnt(2)
	v_mfma_f32_16x16x32_bf16 v[12:15], v[210:213], v[214:217], v[12:15]
	v_mfma_f32_16x16x32_bf16 v[20:23], v[198:201], v[218:221], v[20:23]
	v_mfma_f32_16x16x32_bf16 v[28:31], v[202:205], v[218:221], v[28:31]
	v_mfma_f32_16x16x32_bf16 v[48:51], v[206:209], v[218:221], v[48:51]
	v_mfma_f32_16x16x32_bf16 v[40:43], v[210:213], v[218:221], v[40:43]
	ds_read_b128 v[214:217], v235 offset:4096
	ds_read_b128 v[218:221], v235 offset:5120
	s_waitcnt lgkmcnt(3)
	v_mfma_f32_16x16x32_bf16 v[52:55], v[198:201], v[222:225], v[52:55]
	v_mfma_f32_16x16x32_bf16 v[56:59], v[202:205], v[222:225], v[56:59]
	v_mfma_f32_16x16x32_bf16 v[72:75], v[206:209], v[222:225], v[72:75]
	v_mfma_f32_16x16x32_bf16 v[68:71], v[210:213], v[222:225], v[68:71]
	s_waitcnt lgkmcnt(2)
	v_mfma_f32_16x16x32_bf16 v[76:79], v[198:201], v[226:229], v[76:79]
	v_mfma_f32_16x16x32_bf16 v[80:83], v[202:205], v[226:229], v[80:83]
	v_mfma_f32_16x16x32_bf16 v[100:103], v[206:209], v[226:229], v[100:103]
	v_mfma_f32_16x16x32_bf16 v[96:99], v[210:213], v[226:229], v[96:99]
	ds_read_b128 v[222:225], v235 offset:6144
	ds_read_b128 v[226:229], v235 offset:7168
	s_waitcnt lgkmcnt(3)
	v_mfma_f32_16x16x32_bf16 v[104:107], v[198:201], v[214:217], v[104:107]
	v_mfma_f32_16x16x32_bf16 v[108:111], v[202:205], v[214:217], v[108:111]
	v_mfma_f32_16x16x32_bf16 v[120:123], v[206:209], v[214:217], v[120:123]
	v_mfma_f32_16x16x32_bf16 v[116:119], v[210:213], v[214:217], v[116:119]
	s_waitcnt lgkmcnt(2)
	v_mfma_f32_16x16x32_bf16 v[124:127], v[198:201], v[218:221], v[124:127]
	v_mfma_f32_16x16x32_bf16 v[112:115], v[202:205], v[218:221], v[112:115]
	v_mfma_f32_16x16x32_bf16 v[92:95], v[206:209], v[218:221], v[92:95]
	v_mfma_f32_16x16x32_bf16 v[88:91], v[210:213], v[218:221], v[88:91]
	s_waitcnt lgkmcnt(0)
	v_add_u32_e32 v235, 0x10000, v141
	v_add_u32_e32 v236, 0x10000, v143
	s_waitcnt vmcnt(4)
	s_barrier
; #define GEMM_WAITV(n) asm volatile("s_waitcnt vmcnt(" #n ")" ::: "memory")
; template <bool SWAP>
; __device__ __forceinline__ void gemm_main(f32x4 (&acc)[8][4], const TP& t, int nk, char* lds) {
;     ...
;   for (int kt = 0; kt < nk - 3; ++kt) {
;     GEMM_WAITV(8);
;     GEMM_STEP(kt, true)
;   }
; #pragma unroll 1
;   for (int kt = nk - 3; kt < nk; ++kt) {
;     const int rem = nk - kt;
;     if (rem == 3) GEMM_WAITV(8); else if (rem == 2) GEMM_WAITV(4); else GEMM_WAITV(0);
;     GEMM_STEP(kt, false)
;   }
;   __builtin_amdgcn_s_barrier();
	ds_read_b128 v[214:217], v235
	ds_read_b128 v[218:221], v235 offset:1024
	v_mfma_f32_16x16x32_bf16 v[84:87], v[198:201], v[222:225], v[84:87]
	v_mfma_f32_16x16x32_bf16 v[36:39], v[198:201], v[226:229], v[36:39]
	ds_read_b128 v[198:201], v236 offset:16384
	v_mfma_f32_16x16x32_bf16 v[64:67], v[202:205], v[222:225], v[64:67]
	v_mfma_f32_16x16x32_bf16 v[32:35], v[202:205], v[226:229], v[32:35]
	ds_read_b128 v[202:205], v236 offset:17408
	v_mfma_f32_16x16x32_bf16 v[60:63], v[206:209], v[222:225], v[60:63]
	v_mfma_f32_16x16x32_bf16 v[24:27], v[206:209], v[226:229], v[24:27]
	ds_read_b128 v[206:209], v236 offset:18432
	v_mfma_f32_16x16x32_bf16 v[44:47], v[210:213], v[222:225], v[44:47]
	v_mfma_f32_16x16x32_bf16 v[8:11], v[210:213], v[226:229], v[8:11]
	ds_read_b128 v[210:213], v236 offset:19456
	ds_read_b128 v[222:225], v235 offset:2048
	ds_read_b128 v[226:229], v235 offset:3072
	s_waitcnt lgkmcnt(5)
	v_mfma_f32_16x16x32_bf16 v[0:3], v[198:201], v[214:217], v[0:3]
	s_waitcnt lgkmcnt(4)
	v_mfma_f32_16x16x32_bf16 v[4:7], v[202:205], v[214:217], v[4:7]
	s_waitcnt lgkmcnt(3)
	v_mfma_f32_16x16x32_bf16 v[16:19], v[206:209], v[214:217], v[16:19]
	s_waitcnt lgkmcnt(2)
	v_mfma_f32_16x16x32_bf16 v[12:15], v[210:213], v[214:217], v[12:15]
	v_mfma_f32_16x16x32_bf16 v[20:23], v[198:201], v[218:221], v[20:23]
	v_mfma_f32_16x16x32_bf16 v[28:31], v[202:205], v[218:221], v[28:31]
	v_mfma_f32_16x16x32_bf16 v[48:51], v[206:209], v[218:221], v[48:51]
	v_mfma_f32_16x16x32_bf16 v[40:43], v[210:213], v[218:221], v[40:43]
	ds_read_b128 v[214:217], v235 offset:4096
	ds_read_b128 v[218:221], v235 offset:5120
	s_waitcnt lgkmcnt(3)
	v_mfma_f32_16x16x32_bf16 v[52:55], v[198:201], v[222:225], v[52:55]
	v_mfma_f32_16x16x32_bf16 v[56:59], v[202:205], v[222:225], v[56:59]
	v_mfma_f32_16x16x32_bf16 v[72:75], v[206:209], v[222:225], v[72:75]
	v_mfma_f32_16x16x32_bf16 v[68:71], v[210:213], v[222:225], v[68:71]
	s_waitcnt lgkmcnt(2)
	v_mfma_f32_16x16x32_bf16 v[76:79], v[198:201], v[226:229], v[76:79]
	v_mfma_f32_16x16x32_bf16 v[80:83], v[202:205], v[226:229], v[80:83]
	v_mfma_f32_16x16x32_bf16 v[100:103], v[206:209], v[226:229], v[100:103]
	v_mfma_f32_16x16x32_bf16 v[96:99], v[210:213], v[226:229], v[96:99]
	ds_read_b128 v[222:225], v235 offset:6144
	ds_read_b128 v[226:229], v235 offset:7168
	s_waitcnt lgkmcnt(3)
	v_mfma_f32_16x16x32_bf16 v[104:107], v[198:201], v[214:217], v[104:107]
	v_mfma_f32_16x16x32_bf16 v[108:111], v[202:205], v[214:217], v[108:111]
	v_mfma_f32_16x16x32_bf16 v[120:123], v[206:209], v[214:217], v[120:123]
	v_mfma_f32_16x16x32_bf16 v[116:119], v[210:213], v[214:217], v[116:119]
	s_waitcnt lgkmcnt(2)
	v_mfma_f32_16x16x32_bf16 v[124:127], v[198:201], v[218:221], v[124:127]
	v_mfma_f32_16x16x32_bf16 v[112:115], v[202:205], v[218:221], v[112:115]
	v_mfma_f32_16x16x32_bf16 v[92:95], v[206:209], v[218:221], v[92:95]
	v_mfma_f32_16x16x32_bf16 v[88:91], v[210:213], v[218:221], v[88:91]
	s_waitcnt lgkmcnt(0)
	v_add_u32_e32 v235, 0x18000, v141
	v_add_u32_e32 v236, 0x18000, v143
	s_waitcnt vmcnt(0)
	s_barrier
	ds_read_b128 v[214:217], v235
	ds_read_b128 v[218:221], v235 offset:1024
	v_mfma_f32_16x16x32_bf16 v[84:87], v[198:201], v[222:225], v[84:87]
	v_mfma_f32_16x16x32_bf16 v[36:39], v[198:201], v[226:229], v[36:39]
	ds_read_b128 v[198:201], v236 offset:16384
	v_mfma_f32_16x16x32_bf16 v[64:67], v[202:205], v[222:225], v[64:67]
	v_mfma_f32_16x16x32_bf16 v[32:35], v[202:205], v[226:229], v[32:35]
	ds_read_b128 v[202:205], v236 offset:17408
	v_mfma_f32_16x16x32_bf16 v[60:63], v[206:209], v[222:225], v[60:63]
	v_mfma_f32_16x16x32_bf16 v[24:27], v[206:209], v[226:229], v[24:27]
	ds_read_b128 v[206:209], v236 offset:18432
	v_mfma_f32_16x16x32_bf16 v[44:47], v[210:213], v[222:225], v[44:47]
	v_mfma_f32_16x16x32_bf16 v[8:11], v[210:213], v[226:229], v[8:11]
	ds_read_b128 v[210:213], v236 offset:19456
	ds_read_b128 v[222:225], v235 offset:2048
	ds_read_b128 v[226:229], v235 offset:3072
	s_waitcnt lgkmcnt(5)
	v_mfma_f32_16x16x32_bf16 v[0:3], v[198:201], v[214:217], v[0:3]
	s_waitcnt lgkmcnt(4)
	v_mfma_f32_16x16x32_bf16 v[4:7], v[202:205], v[214:217], v[4:7]
	s_waitcnt lgkmcnt(3)
	v_mfma_f32_16x16x32_bf16 v[16:19], v[206:209], v[214:217], v[16:19]
	s_waitcnt lgkmcnt(2)
	v_mfma_f32_16x16x32_bf16 v[12:15], v[210:213], v[214:217], v[12:15]
	v_mfma_f32_16x16x32_bf16 v[20:23], v[198:201], v[218:221], v[20:23]
	v_mfma_f32_16x16x32_bf16 v[28:31], v[202:205], v[218:221], v[28:31]
	v_mfma_f32_16x16x32_bf16 v[48:51], v[206:209], v[218:221], v[48:51]
	v_mfma_f32_16x16x32_bf16 v[40:43], v[210:213], v[218:221], v[40:43]
	ds_read_b128 v[214:217], v235 offset:4096
	ds_read_b128 v[218:221], v235 offset:5120
	s_waitcnt lgkmcnt(3)
	v_mfma_f32_16x16x32_bf16 v[52:55], v[198:201], v[222:225], v[52:55]
	v_mfma_f32_16x16x32_bf16 v[56:59], v[202:205], v[222:225], v[56:59]
	v_mfma_f32_16x16x32_bf16 v[72:75], v[206:209], v[222:225], v[72:75]
	v_mfma_f32_16x16x32_bf16 v[68:71], v[210:213], v[222:225], v[68:71]
	s_waitcnt lgkmcnt(2)
	v_mfma_f32_16x16x32_bf16 v[76:79], v[198:201], v[226:229], v[76:79]
	v_mfma_f32_16x16x32_bf16 v[80:83], v[202:205], v[226:229], v[80:83]
	v_mfma_f32_16x16x32_bf16 v[100:103], v[206:209], v[226:229], v[100:103]
	v_mfma_f32_16x16x32_bf16 v[96:99], v[210:213], v[226:229], v[96:99]
	ds_read_b128 v[222:225], v235 offset:6144
	ds_read_b128 v[226:229], v235 offset:7168
	s_waitcnt lgkmcnt(3)
	v_mfma_f32_16x16x32_bf16 v[104:107], v[198:201], v[214:217], v[104:107]
	v_mfma_f32_16x16x32_bf16 v[108:111], v[202:205], v[214:217], v[108:111]
	v_mfma_f32_16x16x32_bf16 v[120:123], v[206:209], v[214:217], v[120:123]
	v_mfma_f32_16x16x32_bf16 v[116:119], v[210:213], v[214:217], v[116:119]
	s_waitcnt lgkmcnt(2)
	v_mfma_f32_16x16x32_bf16 v[124:127], v[198:201], v[218:221], v[124:127]
	v_mfma_f32_16x16x32_bf16 v[112:115], v[202:205], v[218:221], v[112:115]
	v_mfma_f32_16x16x32_bf16 v[92:95], v[206:209], v[218:221], v[92:95]
	v_mfma_f32_16x16x32_bf16 v[88:91], v[210:213], v[218:221], v[88:91]
	s_waitcnt lgkmcnt(0)
	v_mfma_f32_16x16x32_bf16 v[84:87], v[198:201], v[222:225], v[84:87]
	v_mfma_f32_16x16x32_bf16 v[36:39], v[198:201], v[226:229], v[36:39]
	v_mfma_f32_16x16x32_bf16 v[64:67], v[202:205], v[222:225], v[64:67]
	v_mfma_f32_16x16x32_bf16 v[32:35], v[202:205], v[226:229], v[32:35]
	v_mfma_f32_16x16x32_bf16 v[60:63], v[206:209], v[222:225], v[60:63]
	v_mfma_f32_16x16x32_bf16 v[24:27], v[206:209], v[226:229], v[24:27]
	v_mfma_f32_16x16x32_bf16 v[44:47], v[210:213], v[222:225], v[44:47]
	v_mfma_f32_16x16x32_bf16 v[8:11], v[210:213], v[226:229], v[8:11]
	s_nop 7

; __device__ __forceinline__ int otid() { int t = threadIdx.x; asm volatile("" : "+v"(t)); return t; }
; #define GEMM_WAITV(n) asm volatile("s_waitcnt vmcnt(" #n ")" ::: "memory")
; template <bool SWAP>
; __device__ __forceinline__ void gemm_main(f32x4 (&acc)[8][4], const TP& t, int nk, char* lds) {
;   const u16* a0 = t.a0; const u16* a1 = t.a1; const u16* b0 = t.b0; const u16* b1 = t.b1;
;   const int tid = otid(), lane = tid & 63, wave = tid >> 6;
;   const int wm = wave >> 2, wn = wave & 3, lr = lane & 15, lq = lane >> 4;
;   const int ldoff = wave * 2048 + lane * 16;
;   const int sw = (lq ^ ((0 - (lr >> 2)) & 3)) << 4;
;   const int aoff = (wm * 128 + lr) * 64 + sw, boff = T_ASTAGE + (wn * 64 + lr) * 64 + sw;
;     ...
; #pragma unroll 1
;   for (int kt = 0; kt < nk - 3; ++kt) {
;     GEMM_WAITV(8);
;     GEMM_STEP(kt, true)
; __device__ __forceinline__ void zero_acc(f32x4 (&acc)[8][4]) {
; #pragma unroll
;   for (int i = 0; i < 8; ++i)
; #pragma unroll
;     for (int j = 0; j < 4; ++j) acc[i][j] = (f32x4){0.f, 0.f, 0.f, 0.f};
.LBB0_938:
	v_mov_b32_e32 v139, v153
	v_mov_b32_e32 v134, v153
	v_mov_b32_e32 v138, v153
	v_mov_b32_e32 v135, v153
	v_mov_b32_e32 v137, v153
	v_mov_b32_e32 v136, v153
	v_mov_b32_e32 v0, v153
	s_mov_b32 s56, s38
	v_lshlrev_b32_e32 v3, 2, v0
	v_and_b32_e32 v3, 48, v3
	v_sub_u32_e32 v3, 0, v3
	v_and_b32_e32 v140, 15, v0
	v_lshlrev_b32_e32 v1, 5, v0
	v_lshlrev_b32_e32 v2, 4, v0
	v_bitop3_b32 v141, v0, 48, v3 bitop3:0x48
	v_ashrrev_i32_e32 v142, 1, v0
	v_lshlrev_b32_e32 v0, 6, v0
	v_and_b32_e32 v1, 0xfffff800, v1
	v_and_b32_e32 v2, 0x3f0, v2
	v_and_or_b32 v3, v142, s54, v140
	v_and_b32_e32 v143, 0x33c0, v0
	v_mov_b32_e32 v0, 0
	v_lshl_or_b32 v144, v3, 6, v141
	v_or_b32_e32 v149, v143, v141
	v_add3_u32 v151, 0, v1, v2
	v_lshl_add_u64 v[128:129], v[146:147], 0, s[26:27]
	v_lshl_add_u64 v[130:131], v[156:157], 0, s[28:29]
	v_lshl_add_u64 v[132:133], v[158:159], 0, s[28:29]
	s_mov_b32 s36, 0x18000
	v_mov_b32_e32 v1, v0
	v_mov_b32_e32 v2, v0
	v_mov_b32_e32 v3, v0
	v_mov_b32_e32 v4, v0
	v_mov_b32_e32 v5, v0
	v_mov_b32_e32 v6, v0
	v_mov_b32_e32 v7, v0
	v_mov_b32_e32 v8, v0
	v_mov_b32_e32 v9, v0
	v_mov_b32_e32 v10, v0
	v_mov_b32_e32 v11, v0
	v_mov_b32_e32 v12, v0
	v_mov_b32_e32 v13, v0
	v_mov_b32_e32 v14, v0
	v_mov_b32_e32 v15, v0
	v_mov_b32_e32 v16, v0
	v_mov_b32_e32 v17, v0
	v_mov_b32_e32 v18, v0
	v_mov_b32_e32 v19, v0
	v_mov_b32_e32 v20, v0
	v_mov_b32_e32 v21, v0
	v_mov_b32_e32 v22, v0
	v_mov_b32_e32 v23, v0
	v_mov_b32_e32 v24, v0
	v_mov_b32_e32 v25, v0
	v_mov_b32_e32 v26, v0
	v_mov_b32_e32 v27, v0
	v_mov_b32_e32 v28, v0
	v_mov_b32_e32 v29, v0
	v_mov_b32_e32 v30, v0
	v_mov_b32_e32 v31, v0
	v_mov_b32_e32 v32, v0
	v_mov_b32_e32 v33, v0
	v_mov_b32_e32 v34, v0
	v_mov_b32_e32 v35, v0
	v_mov_b32_e32 v36, v0
	v_mov_b32_e32 v37, v0
	v_mov_b32_e32 v38, v0
	v_mov_b32_e32 v39, v0
	v_mov_b32_e32 v40, v0
	v_mov_b32_e32 v41, v0
	v_mov_b32_e32 v42, v0
	v_mov_b32_e32 v43, v0
	v_mov_b32_e32 v44, v0
	v_mov_b32_e32 v45, v0
	v_mov_b32_e32 v46, v0
	v_mov_b32_e32 v47, v0
	v_mov_b32_e32 v48, v0
	v_mov_b32_e32 v49, v0
	v_mov_b32_e32 v50, v0
	v_mov_b32_e32 v51, v0
	v_mov_b32_e32 v52, v0
	v_mov_b32_e32 v53, v0
	v_mov_b32_e32 v54, v0
	v_mov_b32_e32 v55, v0
	v_mov_b32_e32 v56, v0
	v_mov_b32_e32 v57, v0
	v_mov_b32_e32 v58, v0
	v_mov_b32_e32 v59, v0
	v_mov_b32_e32 v60, v0
	v_mov_b32_e32 v61, v0
	v_mov_b32_e32 v62, v0
	v_mov_b32_e32 v63, v0
	v_mov_b32_e32 v64, v0
	v_mov_b32_e32 v65, v0
	v_mov_b32_e32 v66, v0
	v_mov_b32_e32 v67, v0
	v_mov_b32_e32 v68, v0
	v_mov_b32_e32 v69, v0
	v_mov_b32_e32 v70, v0
	v_mov_b32_e32 v71, v0
	v_mov_b32_e32 v72, v0
	v_mov_b32_e32 v73, v0
	v_mov_b32_e32 v74, v0
	v_mov_b32_e32 v75, v0
	v_mov_b32_e32 v76, v0
	v_mov_b32_e32 v77, v0
	v_mov_b32_e32 v78, v0
	v_mov_b32_e32 v79, v0
	v_mov_b32_e32 v80, v0
	v_mov_b32_e32 v81, v0
	v_mov_b32_e32 v82, v0
	v_mov_b32_e32 v83, v0
	v_mov_b32_e32 v84, v0
	v_mov_b32_e32 v85, v0
	v_mov_b32_e32 v86, v0
	v_mov_b32_e32 v87, v0
	v_mov_b32_e32 v88, v0
	v_mov_b32_e32 v89, v0
	v_mov_b32_e32 v90, v0
	v_mov_b32_e32 v91, v0
	v_mov_b32_e32 v92, v0
	v_mov_b32_e32 v93, v0
	v_mov_b32_e32 v94, v0
	v_mov_b32_e32 v95, v0
	v_mov_b32_e32 v96, v0
	v_mov_b32_e32 v97, v0
	v_mov_b32_e32 v98, v0
	v_mov_b32_e32 v99, v0
	v_mov_b32_e32 v100, v0
	v_mov_b32_e32 v101, v0
	v_mov_b32_e32 v102, v0
	v_mov_b32_e32 v103, v0
	v_mov_b32_e32 v104, v0
	v_mov_b32_e32 v105, v0
	v_mov_b32_e32 v106, v0
	v_mov_b32_e32 v107, v0
	v_mov_b32_e32 v108, v0
	v_mov_b32_e32 v109, v0
	v_mov_b32_e32 v110, v0
	v_mov_b32_e32 v111, v0
	v_mov_b32_e32 v112, v0
	v_mov_b32_e32 v113, v0
	v_mov_b32_e32 v114, v0
	v_mov_b32_e32 v115, v0
	v_mov_b32_e32 v116, v0
	v_mov_b32_e32 v117, v0
	v_mov_b32_e32 v118, v0
	v_mov_b32_e32 v119, v0
	v_mov_b32_e32 v120, v0
	v_mov_b32_e32 v121, v0
	v_mov_b32_e32 v122, v0
	v_mov_b32_e32 v123, v0
	v_mov_b32_e32 v124, v0
	v_mov_b32_e32 v125, v0
	v_mov_b32_e32 v126, v0
	v_mov_b32_e32 v127, v0
	v_readfirstlane_b32 s98, v151
	s_add_i32 s37, s36, 0xfffe8000
	s_and_b32 s37, s37, 0x18000
	v_add_u32_e32 v235, s37, v144
	v_add_u32_e32 v236, s37, v149
	s_waitcnt vmcnt(8)
	s_barrier
	ds_read_b128 v[174:177], v235
	ds_read_b128 v[178:181], v235 offset:1024
	ds_read_b128 v[156:159], v236 offset:16384
	ds_read_b128 v[160:163], v236 offset:17408
	ds_read_b128 v[164:167], v236 offset:18432
	ds_read_b128 v[170:173], v236 offset:19456
	ds_read_b128 v[182:185], v235 offset:2048
	ds_read_b128 v[186:189], v235 offset:3072
	s_branch .Lg3_mid
.Lg3_top:
	s_add_i32 s37, s36, 0xfffe8000
	s_and_b32 s37, s37, 0x18000
	v_add_u32_e32 v235, s37, v144
	v_add_u32_e32 v236, s37, v149
	s_waitcnt vmcnt(8)
	s_barrier
	ds_read_b128 v[174:177], v235
	ds_read_b128 v[178:181], v235 offset:1024
	v_mfma_f32_16x16x32_bf16 v[28:31], v[156:159], v[182:185], v[28:31]
	v_mfma_f32_16x16x32_bf16 v[12:15], v[156:159], v[186:189], v[12:15]
	ds_read_b128 v[156:159], v236 offset:16384
	v_mfma_f32_16x16x32_bf16 v[24:27], v[160:163], v[182:185], v[24:27]
	v_mfma_f32_16x16x32_bf16 v[8:11], v[160:163], v[186:189], v[8:11]
	ds_read_b128 v[160:163], v236 offset:17408
	v_mfma_f32_16x16x32_bf16 v[20:23], v[164:167], v[182:185], v[20:23]
	v_mfma_f32_16x16x32_bf16 v[4:7], v[164:167], v[186:189], v[4:7]
	ds_read_b128 v[164:167], v236 offset:18432
	v_mfma_f32_16x16x32_bf16 v[16:19], v[170:173], v[182:185], v[16:19]
	v_mfma_f32_16x16x32_bf16 v[0:3], v[170:173], v[186:189], v[0:3]
	ds_read_b128 v[170:173], v236 offset:19456
	ds_read_b128 v[182:185], v235 offset:2048
	ds_read_b128 v[186:189], v235 offset:3072
; __device__ __forceinline__ int otid() { int t = threadIdx.x; asm volatile("" : "+v"(t)); return t; }
; #define GEMM_WAITV(n) asm volatile("s_waitcnt vmcnt(" #n ")" ::: "memory")
; template <bool SWAP>
; __device__ __forceinline__ void gemm_main(f32x4 (&acc)[8][4], const TP& t, int nk, char* lds) {
;   const u16* a0 = t.a0; const u16* a1 = t.a1; const u16* b0 = t.b0; const u16* b1 = t.b1;
;   const int tid = otid(), lane = tid & 63, wave = tid >> 6;
;   const int wm = wave >> 2, wn = wave & 3, lr = lane & 15, lq = lane >> 4;
;   const int ldoff = wave * 2048 + lane * 16;
;   const int sw = (lq ^ ((0 - (lr >> 2)) & 3)) << 4;
;   const int aoff = (wm * 128 + lr) * 64 + sw, boff = T_ASTAGE + (wn * 64 + lr) * 64 + sw;
;     ...
; #pragma unroll 1
;   for (int kt = 0; kt < nk - 3; ++kt) {
;     GEMM_WAITV(8);
;     GEMM_STEP(kt, true)
;   }
; #pragma unroll 1
;   for (int kt = nk - 3; kt < nk; ++kt) {
;     const int rem = nk - kt;
;     if (rem == 3) GEMM_WAITV(8); else if (rem == 2) GEMM_WAITV(4); else GEMM_WAITV(0);
;     GEMM_STEP(kt, false)
;   }
.Lg3_mid:
	s_and_b32 s37, s36, 0x18000
	s_add_i32 s37, s37, s98
	s_mov_b32 m0, s37
	v_lshl_add_u64 v[238:239], v[128:129], 0, s[30:31]
	s_waitcnt lgkmcnt(5)
	v_mfma_f32_16x16x32_bf16 v[124:127], v[156:159], v[174:177], v[124:127]
	global_load_lds_dwordx4 v[238:239], off
	s_waitcnt lgkmcnt(4)
	v_mfma_f32_16x16x32_bf16 v[120:123], v[160:163], v[174:177], v[120:123]
	s_waitcnt lgkmcnt(3)
	v_mfma_f32_16x16x32_bf16 v[116:119], v[164:167], v[174:177], v[116:119]
	s_waitcnt lgkmcnt(2)
	v_mfma_f32_16x16x32_bf16 v[112:115], v[170:173], v[174:177], v[112:115]
	v_mfma_f32_16x16x32_bf16 v[108:111], v[156:159], v[178:181], v[108:111]
	v_mfma_f32_16x16x32_bf16 v[104:107], v[160:163], v[178:181], v[104:107]
	v_mfma_f32_16x16x32_bf16 v[100:103], v[164:167], v[178:181], v[100:103]
	v_mfma_f32_16x16x32_bf16 v[96:99], v[170:173], v[178:181], v[96:99]
	ds_read_b128 v[174:177], v235 offset:4096
	ds_read_b128 v[178:181], v235 offset:5120
	s_add_i32 m0, s37, 0x400
	s_waitcnt lgkmcnt(3)
	v_mfma_f32_16x16x32_bf16 v[92:95], v[156:159], v[182:185], v[92:95]
	global_load_lds_dwordx4 v[128:129], off
	v_mfma_f32_16x16x32_bf16 v[88:91], v[160:163], v[182:185], v[88:91]
	v_mfma_f32_16x16x32_bf16 v[84:87], v[164:167], v[182:185], v[84:87]
	v_mfma_f32_16x16x32_bf16 v[80:83], v[170:173], v[182:185], v[80:83]
	s_waitcnt lgkmcnt(2)
	v_mfma_f32_16x16x32_bf16 v[76:79], v[156:159], v[186:189], v[76:79]
	v_mfma_f32_16x16x32_bf16 v[72:75], v[160:163], v[186:189], v[72:75]
	v_mfma_f32_16x16x32_bf16 v[68:71], v[164:167], v[186:189], v[68:71]
	v_mfma_f32_16x16x32_bf16 v[64:67], v[170:173], v[186:189], v[64:67]
	ds_read_b128 v[182:185], v235 offset:6144
	ds_read_b128 v[186:189], v235 offset:7168
	s_add_i32 m0, s37, 0x4000
	s_waitcnt lgkmcnt(3)
	v_mfma_f32_16x16x32_bf16 v[60:63], v[156:159], v[174:177], v[60:63]
	global_load_lds_dwordx4 v[130:131], off
	v_mfma_f32_16x16x32_bf16 v[56:59], v[160:163], v[174:177], v[56:59]
	v_mfma_f32_16x16x32_bf16 v[52:55], v[164:167], v[174:177], v[52:55]
	v_mfma_f32_16x16x32_bf16 v[48:51], v[170:173], v[174:177], v[48:51]
	s_add_i32 m0, s37, 0x4400
	s_waitcnt lgkmcnt(2)
	v_mfma_f32_16x16x32_bf16 v[44:47], v[156:159], v[178:181], v[44:47]
	global_load_lds_dwordx4 v[132:133], off
	v_mfma_f32_16x16x32_bf16 v[40:43], v[160:163], v[178:181], v[40:43]
	v_lshl_add_u64 v[128:129], v[128:129], 0, 64
	v_lshl_add_u64 v[130:131], v[130:131], 0, 64
	v_lshl_add_u64 v[132:133], v[132:133], 0, 64
	s_add_i32 s36, s36, 0x8000
	v_mfma_f32_16x16x32_bf16 v[36:39], v[164:167], v[178:181], v[36:39]
	v_mfma_f32_16x16x32_bf16 v[32:35], v[170:173], v[178:181], v[32:35]
	s_waitcnt lgkmcnt(0)
	s_cmp_lg_u32 s36, 0x100000
	s_cbranch_scc1 .Lg3_top
	v_add_u32_e32 v235, 0x8000, v144
	v_add_u32_e32 v236, 0x8000, v149
	s_waitcnt vmcnt(8)
	s_barrier
	ds_read_b128 v[174:177], v235
	ds_read_b128 v[178:181], v235 offset:1024
	v_mfma_f32_16x16x32_bf16 v[28:31], v[156:159], v[182:185], v[28:31]
	v_mfma_f32_16x16x32_bf16 v[12:15], v[156:159], v[186:189], v[12:15]
	ds_read_b128 v[156:159], v236 offset:16384
	v_mfma_f32_16x16x32_bf16 v[24:27], v[160:163], v[182:185], v[24:27]
	v_mfma_f32_16x16x32_bf16 v[8:11], v[160:163], v[186:189], v[8:11]
	ds_read_b128 v[160:163], v236 offset:17408
	v_mfma_f32_16x16x32_bf16 v[20:23], v[164:167], v[182:185], v[20:23]
	v_mfma_f32_16x16x32_bf16 v[4:7], v[164:167], v[186:189], v[4:7]
	ds_read_b128 v[164:167], v236 offset:18432
	v_mfma_f32_16x16x32_bf16 v[16:19], v[170:173], v[182:185], v[16:19]
	v_mfma_f32_16x16x32_bf16 v[0:3], v[170:173], v[186:189], v[0:3]
	ds_read_b128 v[170:173], v236 offset:19456
	ds_read_b128 v[182:185], v235 offset:2048
	ds_read_b128 v[186:189], v235 offset:3072
	s_waitcnt lgkmcnt(5)
	v_mfma_f32_16x16x32_bf16 v[124:127], v[156:159], v[174:177], v[124:127]
	s_waitcnt lgkmcnt(4)
	v_mfma_f32_16x16x32_bf16 v[120:123], v[160:163], v[174:177], v[120:123]
	s_waitcnt lgkmcnt(3)
	v_mfma_f32_16x16x32_bf16 v[116:119], v[164:167], v[174:177], v[116:119]
	s_waitcnt lgkmcnt(2)
	v_mfma_f32_16x16x32_bf16 v[112:115], v[170:173], v[174:177], v[112:115]
	v_mfma_f32_16x16x32_bf16 v[108:111], v[156:159], v[178:181], v[108:111]
	v_mfma_f32_16x16x32_bf16 v[104:107], v[160:163], v[178:181], v[104:107]
	v_mfma_f32_16x16x32_bf16 v[100:103], v[164:167], v[178:181], v[100:103]
	v_mfma_f32_16x16x32_bf16 v[96:99], v[170:173], v[178:181], v[96:99]
	ds_read_b128 v[174:177], v235 offset:4096
	ds_read_b128 v[178:181], v235 offset:5120
	s_waitcnt lgkmcnt(3)
	v_mfma_f32_16x16x32_bf16 v[92:95], v[156:159], v[182:185], v[92:95]
	v_mfma_f32_16x16x32_bf16 v[88:91], v[160:163], v[182:185], v[88:91]
	v_mfma_f32_16x16x32_bf16 v[84:87], v[164:167], v[182:185], v[84:87]
	v_mfma_f32_16x16x32_bf16 v[80:83], v[170:173], v[182:185], v[80:83]
	s_waitcnt lgkmcnt(2)
	v_mfma_f32_16x16x32_bf16 v[76:79], v[156:159], v[186:189], v[76:79]
	v_mfma_f32_16x16x32_bf16 v[72:75], v[160:163], v[186:189], v[72:75]
	v_mfma_f32_16x16x32_bf16 v[68:71], v[164:167], v[186:189], v[68:71]
	v_mfma_f32_16x16x32_bf16 v[64:67], v[170:173], v[186:189], v[64:67]
	ds_read_b128 v[182:185], v235 offset:6144
	ds_read_b128 v[186:189], v235 offset:7168
	s_waitcnt lgkmcnt(3)
	v_mfma_f32_16x16x32_bf16 v[60:63], v[156:159], v[174:177], v[60:63]
	v_mfma_f32_16x16x32_bf16 v[56:59], v[160:163], v[174:177], v[56:59]
	v_mfma_f32_16x16x32_bf16 v[52:55], v[164:167], v[174:177], v[52:55]
	v_mfma_f32_16x16x32_bf16 v[48:51], v[170:173], v[174:177], v[48:51]
	s_waitcnt lgkmcnt(2)
	v_mfma_f32_16x16x32_bf16 v[44:47], v[156:159], v[178:181], v[44:47]
	v_mfma_f32_16x16x32_bf16 v[40:43], v[160:163], v[178:181], v[40:43]
	v_mfma_f32_16x16x32_bf16 v[36:39], v[164:167], v[178:181], v[36:39]
	v_mfma_f32_16x16x32_bf16 v[32:35], v[170:173], v[178:181], v[32:35]
	s_waitcnt lgkmcnt(0)
	v_add_u32_e32 v235, 0x10000, v144
	v_add_u32_e32 v236, 0x10000, v149
	s_waitcnt vmcnt(4)
	s_barrier
; #define GEMM_WAITV(n) asm volatile("s_waitcnt vmcnt(" #n ")" ::: "memory")
; template <bool SWAP>
; __device__ __forceinline__ void gemm_main(f32x4 (&acc)[8][4], const TP& t, int nk, char* lds) {
;     ...
; #pragma unroll 1
;   for (int kt = nk - 3; kt < nk; ++kt) {
;     const int rem = nk - kt;
;     if (rem == 3) GEMM_WAITV(8); else if (rem == 2) GEMM_WAITV(4); else GEMM_WAITV(0);
;     GEMM_STEP(kt, false)
;   }
;   __builtin_amdgcn_s_barrier();
	ds_read_b128 v[174:177], v235
	ds_read_b128 v[178:181], v235 offset:1024
	v_mfma_f32_16x16x32_bf16 v[28:31], v[156:159], v[182:185], v[28:31]
	v_mfma_f32_16x16x32_bf16 v[12:15], v[156:159], v[186:189], v[12:15]
	ds_read_b128 v[156:159], v236 offset:16384
	v_mfma_f32_16x16x32_bf16 v[24:27], v[160:163], v[182:185], v[24:27]
	v_mfma_f32_16x16x32_bf16 v[8:11], v[160:163], v[186:189], v[8:11]
	ds_read_b128 v[160:163], v236 offset:17408
	v_mfma_f32_16x16x32_bf16 v[20:23], v[164:167], v[182:185], v[20:23]
	v_mfma_f32_16x16x32_bf16 v[4:7], v[164:167], v[186:189], v[4:7]
	ds_read_b128 v[164:167], v236 offset:18432
	v_mfma_f32_16x16x32_bf16 v[16:19], v[170:173], v[182:185], v[16:19]
	v_mfma_f32_16x16x32_bf16 v[0:3], v[170:173], v[186:189], v[0:3]
	ds_read_b128 v[170:173], v236 offset:19456
	ds_read_b128 v[182:185], v235 offset:2048
	ds_read_b128 v[186:189], v235 offset:3072
	s_waitcnt lgkmcnt(5)
	v_mfma_f32_16x16x32_bf16 v[124:127], v[156:159], v[174:177], v[124:127]
	s_waitcnt lgkmcnt(4)
	v_mfma_f32_16x16x32_bf16 v[120:123], v[160:163], v[174:177], v[120:123]
	s_waitcnt lgkmcnt(3)
	v_mfma_f32_16x16x32_bf16 v[116:119], v[164:167], v[174:177], v[116:119]
	s_waitcnt lgkmcnt(2)
	v_mfma_f32_16x16x32_bf16 v[112:115], v[170:173], v[174:177], v[112:115]
	v_mfma_f32_16x16x32_bf16 v[108:111], v[156:159], v[178:181], v[108:111]
	v_mfma_f32_16x16x32_bf16 v[104:107], v[160:163], v[178:181], v[104:107]
	v_mfma_f32_16x16x32_bf16 v[100:103], v[164:167], v[178:181], v[100:103]
	v_mfma_f32_16x16x32_bf16 v[96:99], v[170:173], v[178:181], v[96:99]
	ds_read_b128 v[174:177], v235 offset:4096
	ds_read_b128 v[178:181], v235 offset:5120
	s_waitcnt lgkmcnt(3)
	v_mfma_f32_16x16x32_bf16 v[92:95], v[156:159], v[182:185], v[92:95]
	v_mfma_f32_16x16x32_bf16 v[88:91], v[160:163], v[182:185], v[88:91]
	v_mfma_f32_16x16x32_bf16 v[84:87], v[164:167], v[182:185], v[84:87]
	v_mfma_f32_16x16x32_bf16 v[80:83], v[170:173], v[182:185], v[80:83]
	s_waitcnt lgkmcnt(2)
	v_mfma_f32_16x16x32_bf16 v[76:79], v[156:159], v[186:189], v[76:79]
	v_mfma_f32_16x16x32_bf16 v[72:75], v[160:163], v[186:189], v[72:75]
	v_mfma_f32_16x16x32_bf16 v[68:71], v[164:167], v[186:189], v[68:71]
	v_mfma_f32_16x16x32_bf16 v[64:67], v[170:173], v[186:189], v[64:67]
	ds_read_b128 v[182:185], v235 offset:6144
	ds_read_b128 v[186:189], v235 offset:7168
	s_waitcnt lgkmcnt(3)
	v_mfma_f32_16x16x32_bf16 v[60:63], v[156:159], v[174:177], v[60:63]
	v_mfma_f32_16x16x32_bf16 v[56:59], v[160:163], v[174:177], v[56:59]
	v_mfma_f32_16x16x32_bf16 v[52:55], v[164:167], v[174:177], v[52:55]
	v_mfma_f32_16x16x32_bf16 v[48:51], v[170:173], v[174:177], v[48:51]
	s_waitcnt lgkmcnt(2)
	v_mfma_f32_16x16x32_bf16 v[44:47], v[156:159], v[178:181], v[44:47]
	v_mfma_f32_16x16x32_bf16 v[40:43], v[160:163], v[178:181], v[40:43]
	v_mfma_f32_16x16x32_bf16 v[36:39], v[164:167], v[178:181], v[36:39]
	v_mfma_f32_16x16x32_bf16 v[32:35], v[170:173], v[178:181], v[32:35]
	s_waitcnt lgkmcnt(0)
	v_add_u32_e32 v235, 0x18000, v144
	v_add_u32_e32 v236, 0x18000, v149
	s_waitcnt vmcnt(0)
	s_barrier
	ds_read_b128 v[174:177], v235
	ds_read_b128 v[178:181], v235 offset:1024
	v_mfma_f32_16x16x32_bf16 v[28:31], v[156:159], v[182:185], v[28:31]
	v_mfma_f32_16x16x32_bf16 v[12:15], v[156:159], v[186:189], v[12:15]
	ds_read_b128 v[156:159], v236 offset:16384
	v_mfma_f32_16x16x32_bf16 v[24:27], v[160:163], v[182:185], v[24:27]
	v_mfma_f32_16x16x32_bf16 v[8:11], v[160:163], v[186:189], v[8:11]
	ds_read_b128 v[160:163], v236 offset:17408
	v_mfma_f32_16x16x32_bf16 v[20:23], v[164:167], v[182:185], v[20:23]
	v_mfma_f32_16x16x32_bf16 v[4:7], v[164:167], v[186:189], v[4:7]
	ds_read_b128 v[164:167], v236 offset:18432
	v_mfma_f32_16x16x32_bf16 v[16:19], v[170:173], v[182:185], v[16:19]
	v_mfma_f32_16x16x32_bf16 v[0:3], v[170:173], v[186:189], v[0:3]
	ds_read_b128 v[170:173], v236 offset:19456
	ds_read_b128 v[182:185], v235 offset:2048
	ds_read_b128 v[186:189], v235 offset:3072
	s_waitcnt lgkmcnt(5)
	v_mfma_f32_16x16x32_bf16 v[124:127], v[156:159], v[174:177], v[124:127]
	s_waitcnt lgkmcnt(4)
	v_mfma_f32_16x16x32_bf16 v[120:123], v[160:163], v[174:177], v[120:123]
	s_waitcnt lgkmcnt(3)
	v_mfma_f32_16x16x32_bf16 v[116:119], v[164:167], v[174:177], v[116:119]
	s_waitcnt lgkmcnt(2)
	v_mfma_f32_16x16x32_bf16 v[112:115], v[170:173], v[174:177], v[112:115]
	v_mfma_f32_16x16x32_bf16 v[108:111], v[156:159], v[178:181], v[108:111]
	v_mfma_f32_16x16x32_bf16 v[104:107], v[160:163], v[178:181], v[104:107]
	v_mfma_f32_16x16x32_bf16 v[100:103], v[164:167], v[178:181], v[100:103]
	v_mfma_f32_16x16x32_bf16 v[96:99], v[170:173], v[178:181], v[96:99]
	ds_read_b128 v[174:177], v235 offset:4096
	ds_read_b128 v[178:181], v235 offset:5120
	s_waitcnt lgkmcnt(3)
	v_mfma_f32_16x16x32_bf16 v[92:95], v[156:159], v[182:185], v[92:95]
	v_mfma_f32_16x16x32_bf16 v[88:91], v[160:163], v[182:185], v[88:91]
	v_mfma_f32_16x16x32_bf16 v[84:87], v[164:167], v[182:185], v[84:87]
	v_mfma_f32_16x16x32_bf16 v[80:83], v[170:173], v[182:185], v[80:83]
	s_waitcnt lgkmcnt(2)
	v_mfma_f32_16x16x32_bf16 v[76:79], v[156:159], v[186:189], v[76:79]
	v_mfma_f32_16x16x32_bf16 v[72:75], v[160:163], v[186:189], v[72:75]
	v_mfma_f32_16x16x32_bf16 v[68:71], v[164:167], v[186:189], v[68:71]
	v_mfma_f32_16x16x32_bf16 v[64:67], v[170:173], v[186:189], v[64:67]
	ds_read_b128 v[182:185], v235 offset:6144
	ds_read_b128 v[186:189], v235 offset:7168
	s_waitcnt lgkmcnt(3)
	v_mfma_f32_16x16x32_bf16 v[60:63], v[156:159], v[174:177], v[60:63]
	v_mfma_f32_16x16x32_bf16 v[56:59], v[160:163], v[174:177], v[56:59]
	v_mfma_f32_16x16x32_bf16 v[52:55], v[164:167], v[174:177], v[52:55]
	v_mfma_f32_16x16x32_bf16 v[48:51], v[170:173], v[174:177], v[48:51]
	s_waitcnt lgkmcnt(2)
	v_mfma_f32_16x16x32_bf16 v[44:47], v[156:159], v[178:181], v[44:47]
	v_mfma_f32_16x16x32_bf16 v[40:43], v[160:163], v[178:181], v[40:43]
	v_mfma_f32_16x16x32_bf16 v[36:39], v[164:167], v[178:181], v[36:39]
	v_mfma_f32_16x16x32_bf16 v[32:35], v[170:173], v[178:181], v[32:35]
	s_waitcnt lgkmcnt(0)
	v_mfma_f32_16x16x32_bf16 v[28:31], v[156:159], v[182:185], v[28:31]
	v_mfma_f32_16x16x32_bf16 v[12:15], v[156:159], v[186:189], v[12:15]
	v_mfma_f32_16x16x32_bf16 v[24:27], v[160:163], v[182:185], v[24:27]
	v_mfma_f32_16x16x32_bf16 v[8:11], v[160:163], v[186:189], v[8:11]
	v_mfma_f32_16x16x32_bf16 v[20:23], v[164:167], v[182:185], v[20:23]
	v_mfma_f32_16x16x32_bf16 v[4:7], v[164:167], v[186:189], v[4:7]
	v_mfma_f32_16x16x32_bf16 v[16:19], v[170:173], v[182:185], v[16:19]
	v_mfma_f32_16x16x32_bf16 v[0:3], v[170:173], v[186:189], v[0:3]
	s_nop 7
